# merged K-loop with balanced staging: 4 LDS-DMA instructions in each load segment (B-half1 staged with A-half1 one K-tile ahead) instead of 2 and 6
# baseline (speedup 1.0000x reference)
; #define BAR() { __builtin_amdgcn_sched_barrier(0); __builtin_amdgcn_s_barrier(); asm volatile("" ::: "memory"); __builtin_amdgcn_sched_barrier(0); }
; DI void gemm_stream2(const bf16_t* __restrict__ A, int lda, const bf16_t* __restrict__ Bt, int ldb, int K, int m0, int n0, ...
;     ...
;     const int wave = __builtin_amdgcn_readfirstlane(tid >> 6), lane = tid & 63, wm = wave >> 1, wn = wave & 1, r = lane & 15, q = lane >> 4;
;     const int sc0 = ((lane & 7) ^ (lane >> 4)) * 8, sc1 = ((lane & 7) ^ (4 | (lane >> 4))) * 8;
;     const bf16_t* ga = A + (size_t)(m0 + wave * 32 + (lane >> 3)) * lda;
;     const bf16_t* gb = Bt + (size_t)(n0 + wave * 16 + (lane >> 3)) * ldb;
;     const bf16_t* gan = An + (size_t)(m0n + wave * 32 + (lane >> 3)) * ldan;
;     const bf16_t* gbn = Btn + (size_t)(n0n + wave * 16 + (lane >> 3)) * ldbn;
;     const unsigned wa = (unsigned)wave * 4096u, wbb = 32768u + (unsigned)wave * 2048u;
;     ...
;     const int sw = r >> 1;
;     const unsigned fo0 = (unsigned)(r * 128 + ((q ^ sw) << 4)), fo1 = (unsigned)(r * 128 + (((q ^ sw) ^ 4) << 4));
;     const unsigned aoff = (unsigned)(wm * 64) * 128u, boff = 32768u + (unsigned)(wn * 64) * 128u;
;     const int nk = K / 64;
;     const int grp = wave >> 2;
;     ...
;     int st = rg.st;
;     if (!rg.primed) {
;         const int s1p = st == 2 ? 0 : st + 1;
;         BAR();
;         STAGE(st, 0);
;         STAGE(s1p, 1);
;         asm volatile("s_waitcnt vmcnt(6)" ::: "memory");
;         BAR();
;     }
;     if (grp == 1) BAR();
;     DI bool next(int& tm, int& tn) {
;         if (L >= end) return false;
;         const int gsz = 8 * ntn, grp = L / gsz, rem = L - grp * gsz, rows = min(8, ntm - grp * 8);
;         tn = rem / rows; tm = grp * 8 + (rem - tn * rows);
;         L += step; return true;
.Lgu_ranged:
	s_cmp_ge_u32 s51, s52
	s_cbranch_scc1 .LBB0_860
	v_and_b32_e32 v190, 63, v193
	v_and_b32_e32 v191, 15, v190
	v_lshrrev_b32_e32 v17, 4, v190
	v_lshrrev_b32_e32 v18, 3, v190
	v_and_b32_e32 v19, 7, v190
	v_xor_b32_e32 v195, v19, v17
	v_lshlrev_b32_e32 v195, 4, v195
	v_lshl_add_u32 v184, v18, 11, v195
	v_or_b32_e32 v195, 4, v17
	v_xor_b32_e32 v195, v19, v195
	v_lshlrev_b32_e32 v195, 4, v195
	v_add_u32_e32 v227, 8, v18
	v_lshl_add_u32 v185, v227, 11, v195
	v_lshrrev_b32_e32 v195, 1, v191
	v_xor_b32_e32 v195, v17, v195
	v_lshlrev_b32_e32 v195, 4, v195
	s_lshl_b32 s1, s33, 6
	v_add_u32_e32 v227, s1, v191
	v_lshl_add_u32 v186, v227, 7, v195
	v_xor_b32_e32 v187, 64, v186
	v_mul_u32_u24_e32 v228, 0x1600, v227
	s_lshl_b32 s1, s36, 5
	v_add_u32_e32 v227, s1, v191
	v_lshl_add_u32 v188, v227, 7, v195
	v_add_u32_e32 v188, 0x10000, v188
	v_xor_b32_e32 v189, 64, v188
	v_lshl_add_u32 v229, v17, 3, s1
	v_add_u32_e32 v237, v228, v229
	v_and_b32_e32 v227, 1, v17
	v_mul_u32_u24_e32 v227, 0x15ff8, v227
	v_add_u32_e32 v237, v237, v227
	s_mul_i32 s1, s51, 0x1745e
	s_lshr_b32 s2, s1, 24
	s_mul_i32 s1, s2, 0xb0
	s_sub_u32 s1, s51, s1
	s_lshr_b32 s3, s1, 3
	s_and_b32 s37, s1, 7
	s_cmp_lt_u32 s2, 8
	s_cselect_b32 s58, s3, s1
	s_cselect_b32 s37, s37, 0
	s_lshl_b32 s2, s2, 3
	s_add_i32 s57, s2, s37
	s_lshl_b32 s1, s57, 19
	s_lshl_b32 s2, s10, 15
	s_add_u32 s1, s1, s2
	s_add_u32 s1, s1, 0x3240000
	s_add_u32 s66, s88, s1
	s_addc_u32 s67, s89, 0
	s_add_u32 s68, s66, 0x40000
	s_addc_u32 s69, s67, 0
	s_lshl_b32 s1, s58, 19
	s_add_u32 s1, s1, s2
	s_add_u32 s1, s1, s61
	s_add_u32 s70, s88, s1
	s_addc_u32 s71, s89, 0
	s_add_u32 s72, s70, 0x40000
	s_addc_u32 s73, s71, 0
	s_add_i32 m0, s39, 0x10000
	s_nop 0
	global_load_lds_dwordx4 v184, s[70:71]
	s_add_i32 m0, s39, 0x10400
	s_nop 0
	global_load_lds_dwordx4 v185, s[70:71]
	s_add_u32 s70, s70, 0x80
	s_addc_u32 s71, s71, 0
	s_add_i32 m0, s39, 0x0
	s_nop 0
	global_load_lds_dwordx4 v184, s[66:67]
	s_add_i32 m0, s39, 0x400
	s_nop 0
	global_load_lds_dwordx4 v185, s[66:67]
	s_add_u32 s66, s66, 0x80
	s_addc_u32 s67, s67, 0
	s_add_i32 m0, s39, 0x14000
	s_nop 0
	global_load_lds_dwordx4 v184, s[72:73]
	s_add_i32 m0, s39, 0x14400
	s_nop 0
	global_load_lds_dwordx4 v185, s[72:73]
	s_add_u32 s72, s72, 0x80
	s_addc_u32 s73, s73, 0
	s_add_i32 m0, s39, 0x4000
	s_nop 0
	global_load_lds_dwordx4 v184, s[68:69]
	s_add_i32 m0, s39, 0x4400
	s_nop 0
	global_load_lds_dwordx4 v185, s[68:69]
	s_add_u32 s68, s68, 0x80
	s_addc_u32 s69, s69, 0
	s_add_i32 m0, s39, 0x18000
	s_nop 0
	global_load_lds_dwordx4 v184, s[70:71]
	s_add_i32 m0, s39, 0x18400
	s_nop 0
	global_load_lds_dwordx4 v185, s[70:71]
	s_add_u32 s70, s70, 0x80
	s_addc_u32 s71, s71, 0
	s_add_i32 m0, s39, 0x8000
	s_nop 0
	global_load_lds_dwordx4 v184, s[66:67]
	s_add_i32 m0, s39, 0x8400
	s_nop 0
	global_load_lds_dwordx4 v185, s[66:67]
	s_add_u32 s66, s66, 0x80
	s_addc_u32 s67, s67, 0
	s_waitcnt vmcnt(6)
	s_barrier
	s_cmp_eq_u32 s33, 0
	s_cbranch_scc1 .Lgu_lead
	s_barrier

; #define LAS __attribute__((address_space(3)))
; #define BAR() { __builtin_amdgcn_sched_barrier(0); __builtin_amdgcn_s_barrier(); asm volatile("" ::: "memory"); __builtin_amdgcn_sched_barrier(0); }
; DI void gemm_stream2(const bf16_t* __restrict__ A, int lda, const bf16_t* __restrict__ Bt, int ldb, int K, int m0, int n0, ...
;     ...
;     for (int kt = 0; kt < nk; ++kt) {
;         const bool pf = (kt + 2 < nk) || has_next, more = (kt + 1 < nk) || has_next;
;         const bf16_t* pa = (kt + 2 < nk) ? ga + (kt + 2) * 64 : gan + (kt + 2 - nk) * 64;
;         const bf16_t* pb = (kt + 2 < nk) ? gb + (kt + 2) * 64 : gbn + (kt + 2 - nk) * 64;
;         const int plda = (kt + 2 < nk) ? lda : ldan, pldb = (kt + 2 < nk) ? ldb : ldbn;
;         const int s2 = st >= 1 ? st - 1 : 2;
;         const LAS char* base = lds + st * 49152;
; #pragma unroll
;         for (int ks = 0; ks < 2; ++ks) {
;             const unsigned fo = ks ? fo1 : fo0;
;             bf16x8 af[4], bfr[4];
; #pragma unroll
;             for (int i = 0; i < 4; ++i) { af[i] = *(const LAS bf16x8*)(base + aoff + i * 2048 + fo); bfr[i] = *(const LAS bf16x8*)(base + boff + i * 2048 + fo); }
;             if (ks == 1 && more) { if (pf) asm volatile("s_waitcnt vmcnt(3)" ::: "memory"); else asm volatile("s_waitcnt vmcnt(0)" ::: "memory"); }
;             if (pf) { PIECE(s2, ks * 3 + 0); PIECE(s2, ks * 3 + 1); PIECE(s2, ks * 3 + 2); }
;             asm volatile("s_waitcnt lgkmcnt(0)" ::: "memory");
;             BAR();
;             __builtin_amdgcn_s_setprio(1);
; #pragma unroll
;             for (int mi = 0; mi < 4; ++mi)
; #pragma unroll
;                 for (int ni = 0; ni < 4; ++ni) acc[mi][ni] = __builtin_amdgcn_mfma_f32_16x16x32_bf16(bfr[ni], af[mi], acc[mi][ni], 0, 0, 0);
;             __builtin_amdgcn_s_setprio(0);
;             BAR();
;         }
.Lgu_kloop:
	ds_read_b128 v[0:3], v188 offset:16
	ds_read_b128 v[4:7], v189 offset:16
	ds_read_b128 v[8:11], v188 offset:2064
	ds_read_b128 v[12:15], v189 offset:2064
	ds_read_b128 v[196:199], v188 offset:16400
	ds_read_b128 v[200:203], v189 offset:16400
	ds_read_b128 v[204:207], v188 offset:18448
	ds_read_b128 v[208:211], v189 offset:18448
	ds_read_b128 v[152:155], v186 offset:16
	ds_read_b128 v[156:159], v187 offset:16
	ds_read_b128 v[160:163], v186 offset:2064
	ds_read_b128 v[164:167], v187 offset:2064
	ds_read_b128 v[168:171], v186 offset:4112
	ds_read_b128 v[172:175], v187 offset:4112
	ds_read_b128 v[176:179], v186 offset:6160
	ds_read_b128 v[180:183], v187 offset:6160
	s_add_i32 m0, s39, 0x1c000
	s_nop 0
	global_load_lds_dwordx4 v184, s[72:73]
	s_add_i32 m0, s39, 0x1c400
	s_nop 0
	global_load_lds_dwordx4 v185, s[72:73]
	s_add_u32 s72, s72, 0x80
	s_addc_u32 s73, s73, 0
	s_add_i32 m0, s39, 0xc000
	s_nop 0
	global_load_lds_dwordx4 v184, s[68:69]
	s_add_i32 m0, s39, 0xc400
	s_nop 0
	global_load_lds_dwordx4 v185, s[68:69]
	s_add_u32 s68, s68, 0x80
	s_addc_u32 s69, s69, 0
	s_waitcnt lgkmcnt(0)
	s_waitcnt vmcnt(8)
	s_barrier
	s_setprio 1
	v_mfma_f32_16x16x32_bf16 v[24:27], v[0:3], v[152:155], v[24:27]
	v_mfma_f32_16x16x32_bf16 v[28:31], v[8:11], v[152:155], v[28:31]
	v_mfma_f32_16x16x32_bf16 v[32:35], v[0:3], v[160:163], v[32:35]
	v_mfma_f32_16x16x32_bf16 v[36:39], v[8:11], v[160:163], v[36:39]
	v_mfma_f32_16x16x32_bf16 v[40:43], v[0:3], v[168:171], v[40:43]
	v_mfma_f32_16x16x32_bf16 v[44:47], v[8:11], v[168:171], v[44:47]
	v_mfma_f32_16x16x32_bf16 v[48:51], v[0:3], v[176:179], v[48:51]
	v_mfma_f32_16x16x32_bf16 v[52:55], v[8:11], v[176:179], v[52:55]
	v_mfma_f32_16x16x32_bf16 v[24:27], v[4:7], v[156:159], v[24:27]
	v_mfma_f32_16x16x32_bf16 v[28:31], v[12:15], v[156:159], v[28:31]
	v_mfma_f32_16x16x32_bf16 v[32:35], v[4:7], v[164:167], v[32:35]
	v_mfma_f32_16x16x32_bf16 v[36:39], v[12:15], v[164:167], v[36:39]
	v_mfma_f32_16x16x32_bf16 v[40:43], v[4:7], v[172:175], v[40:43]
	v_mfma_f32_16x16x32_bf16 v[44:47], v[12:15], v[172:175], v[44:47]
	v_mfma_f32_16x16x32_bf16 v[48:51], v[4:7], v[180:183], v[48:51]
	v_mfma_f32_16x16x32_bf16 v[52:55], v[12:15], v[180:183], v[52:55]
	v_mfma_f32_16x16x32_bf16 v[56:59], v[196:199], v[152:155], v[56:59]
	v_mfma_f32_16x16x32_bf16 v[60:63], v[204:207], v[152:155], v[60:63]
	v_mfma_f32_16x16x32_bf16 v[64:67], v[196:199], v[160:163], v[64:67]
	v_mfma_f32_16x16x32_bf16 v[68:71], v[204:207], v[160:163], v[68:71]
	v_mfma_f32_16x16x32_bf16 v[72:75], v[196:199], v[168:171], v[72:75]
	v_mfma_f32_16x16x32_bf16 v[76:79], v[204:207], v[168:171], v[76:79]
	v_mfma_f32_16x16x32_bf16 v[80:83], v[196:199], v[176:179], v[80:83]
	v_mfma_f32_16x16x32_bf16 v[84:87], v[204:207], v[176:179], v[84:87]
	v_mfma_f32_16x16x32_bf16 v[56:59], v[200:203], v[156:159], v[56:59]
	v_mfma_f32_16x16x32_bf16 v[60:63], v[208:211], v[156:159], v[60:63]
	v_mfma_f32_16x16x32_bf16 v[64:67], v[200:203], v[164:167], v[64:67]
	v_mfma_f32_16x16x32_bf16 v[68:71], v[208:211], v[164:167], v[68:71]
	v_mfma_f32_16x16x32_bf16 v[72:75], v[200:203], v[172:175], v[72:75]
	v_mfma_f32_16x16x32_bf16 v[76:79], v[208:211], v[172:175], v[76:79]
	v_mfma_f32_16x16x32_bf16 v[80:83], v[200:203], v[180:183], v[80:83]
	v_mfma_f32_16x16x32_bf16 v[84:87], v[208:211], v[180:183], v[84:87]
	s_setprio 0
	s_barrier
	ds_read_b128 v[152:155], v186 offset:16400
	ds_read_b128 v[156:159], v187 offset:16400
	ds_read_b128 v[160:163], v186 offset:18448
	ds_read_b128 v[164:167], v187 offset:18448
	ds_read_b128 v[168:171], v186 offset:20496
	ds_read_b128 v[172:175], v187 offset:20496
	ds_read_b128 v[176:179], v186 offset:22544
	ds_read_b128 v[180:183], v187 offset:22544
	s_cmp_lg_u32 s0, s54
	s_cbranch_scc1 .Lgu_nosw1
	s_mov_b64 s[66:67], s[74:75]
	s_mov_b64 s[70:71], s[80:81]
.Lgu_nosw1:
	s_add_i32 m0, s39, 0x10000
	s_nop 0
	global_load_lds_dwordx4 v184, s[70:71]
	s_add_i32 m0, s39, 0x10400
	s_nop 0
	global_load_lds_dwordx4 v185, s[70:71]
	s_add_u32 s70, s70, 0x80
	s_addc_u32 s71, s71, 0
	s_add_i32 m0, s39, 0x0
	s_nop 0
	global_load_lds_dwordx4 v184, s[66:67]
	s_add_i32 m0, s39, 0x400
	s_nop 0
	global_load_lds_dwordx4 v185, s[66:67]
	s_add_u32 s66, s66, 0x80
	s_addc_u32 s67, s67, 0
	s_waitcnt lgkmcnt(0)
	s_waitcnt vmcnt(6)
	s_barrier
	s_setprio 1
	v_mfma_f32_16x16x32_bf16 v[88:91], v[0:3], v[152:155], v[88:91]
	v_mfma_f32_16x16x32_bf16 v[92:95], v[8:11], v[152:155], v[92:95]
	v_mfma_f32_16x16x32_bf16 v[96:99], v[0:3], v[160:163], v[96:99]
	v_mfma_f32_16x16x32_bf16 v[100:103], v[8:11], v[160:163], v[100:103]
	v_mfma_f32_16x16x32_bf16 v[104:107], v[0:3], v[168:171], v[104:107]
	v_mfma_f32_16x16x32_bf16 v[108:111], v[8:11], v[168:171], v[108:111]
	v_mfma_f32_16x16x32_bf16 v[112:115], v[0:3], v[176:179], v[112:115]
	v_mfma_f32_16x16x32_bf16 v[116:119], v[8:11], v[176:179], v[116:119]
	v_mfma_f32_16x16x32_bf16 v[88:91], v[4:7], v[156:159], v[88:91]
	v_mfma_f32_16x16x32_bf16 v[92:95], v[12:15], v[156:159], v[92:95]
	v_mfma_f32_16x16x32_bf16 v[96:99], v[4:7], v[164:167], v[96:99]
	v_mfma_f32_16x16x32_bf16 v[100:103], v[12:15], v[164:167], v[100:103]
	v_mfma_f32_16x16x32_bf16 v[104:107], v[4:7], v[172:175], v[104:107]
	v_mfma_f32_16x16x32_bf16 v[108:111], v[12:15], v[172:175], v[108:111]
	v_mfma_f32_16x16x32_bf16 v[112:115], v[4:7], v[180:183], v[112:115]
	v_mfma_f32_16x16x32_bf16 v[116:119], v[12:15], v[180:183], v[116:119]
	v_mfma_f32_16x16x32_bf16 v[120:123], v[196:199], v[152:155], v[120:123]
	v_mfma_f32_16x16x32_bf16 v[124:127], v[204:207], v[152:155], v[124:127]
	v_mfma_f32_16x16x32_bf16 v[128:131], v[196:199], v[160:163], v[128:131]
	v_mfma_f32_16x16x32_bf16 v[132:135], v[204:207], v[160:163], v[132:135]
	v_mfma_f32_16x16x32_bf16 v[136:139], v[196:199], v[168:171], v[136:139]
	v_mfma_f32_16x16x32_bf16 v[140:143], v[204:207], v[168:171], v[140:143]
	v_mfma_f32_16x16x32_bf16 v[144:147], v[196:199], v[176:179], v[144:147]
	v_mfma_f32_16x16x32_bf16 v[148:151], v[204:207], v[176:179], v[148:151]
	v_mfma_f32_16x16x32_bf16 v[120:123], v[200:203], v[156:159], v[120:123]
	v_mfma_f32_16x16x32_bf16 v[124:127], v[208:211], v[156:159], v[124:127]
	v_mfma_f32_16x16x32_bf16 v[128:131], v[200:203], v[164:167], v[128:131]
	v_mfma_f32_16x16x32_bf16 v[132:135], v[208:211], v[164:167], v[132:135]
	v_mfma_f32_16x16x32_bf16 v[136:139], v[200:203], v[172:175], v[136:139]
	v_mfma_f32_16x16x32_bf16 v[140:143], v[208:211], v[172:175], v[140:143]
	v_mfma_f32_16x16x32_bf16 v[144:147], v[200:203], v[180:183], v[144:147]
	v_mfma_f32_16x16x32_bf16 v[148:151], v[208:211], v[180:183], v[148:151]
	s_setprio 0
	s_barrier
; #define LAS __attribute__((address_space(3)))
; #define BAR() { __builtin_amdgcn_sched_barrier(0); __builtin_amdgcn_s_barrier(); asm volatile("" ::: "memory"); __builtin_amdgcn_sched_barrier(0); }
; DI void gemm_stream2(const bf16_t* __restrict__ A, int lda, const bf16_t* __restrict__ Bt, int ldb, int K, int m0, int n0, ...
;     ...
;     for (int kt = 0; kt < nk; ++kt) {
;         const bool pf = (kt + 2 < nk) || has_next, more = (kt + 1 < nk) || has_next;
;         const bf16_t* pa = (kt + 2 < nk) ? ga + (kt + 2) * 64 : gan + (kt + 2 - nk) * 64;
;         const bf16_t* pb = (kt + 2 < nk) ? gb + (kt + 2) * 64 : gbn + (kt + 2 - nk) * 64;
;         const int plda = (kt + 2 < nk) ? lda : ldan, pldb = (kt + 2 < nk) ? ldb : ldbn;
;         const int s2 = st >= 1 ? st - 1 : 2;
;         const LAS char* base = lds + st * 49152;
; #pragma unroll
;         for (int ks = 0; ks < 2; ++ks) {
;             const unsigned fo = ks ? fo1 : fo0;
;             bf16x8 af[4], bfr[4];
; #pragma unroll
;             for (int i = 0; i < 4; ++i) { af[i] = *(const LAS bf16x8*)(base + aoff + i * 2048 + fo); bfr[i] = *(const LAS bf16x8*)(base + boff + i * 2048 + fo); }
;             if (ks == 1 && more) { if (pf) asm volatile("s_waitcnt vmcnt(3)" ::: "memory"); else asm volatile("s_waitcnt vmcnt(0)" ::: "memory"); }
;             if (pf) { PIECE(s2, ks * 3 + 0); PIECE(s2, ks * 3 + 1); PIECE(s2, ks * 3 + 2); }
;             asm volatile("s_waitcnt lgkmcnt(0)" ::: "memory");
;             BAR();
;             __builtin_amdgcn_s_setprio(1);
; #pragma unroll
;             for (int mi = 0; mi < 4; ++mi)
; #pragma unroll
;                 for (int ni = 0; ni < 4; ++ni) acc[mi][ni] = __builtin_amdgcn_mfma_f32_16x16x32_bf16(bfr[ni], af[mi], acc[mi][ni], 0, 0, 0);
;             __builtin_amdgcn_s_setprio(0);
;             BAR();
;         }
	ds_read_b128 v[0:3], v188 offset:32784
	ds_read_b128 v[4:7], v189 offset:32784
	ds_read_b128 v[8:11], v188 offset:34832
	ds_read_b128 v[12:15], v189 offset:34832
	ds_read_b128 v[196:199], v188 offset:49168
	ds_read_b128 v[200:203], v189 offset:49168
	ds_read_b128 v[204:207], v188 offset:51216
	ds_read_b128 v[208:211], v189 offset:51216
	ds_read_b128 v[152:155], v186 offset:32784
	ds_read_b128 v[156:159], v187 offset:32784
	ds_read_b128 v[160:163], v186 offset:34832
	ds_read_b128 v[164:167], v187 offset:34832
	ds_read_b128 v[168:171], v186 offset:36880
	ds_read_b128 v[172:175], v187 offset:36880
	ds_read_b128 v[176:179], v186 offset:38928
	ds_read_b128 v[180:183], v187 offset:38928
	s_cmp_lg_u32 s0, s54
	s_cbranch_scc1 .Lgu_nosw2
	s_mov_b64 s[68:69], s[78:79]
	s_mov_b64 s[72:73], s[82:83]
.Lgu_nosw2:
	s_add_i32 m0, s39, 0x14000
	s_nop 0
	global_load_lds_dwordx4 v184, s[72:73]
	s_add_i32 m0, s39, 0x14400
	s_nop 0
	global_load_lds_dwordx4 v185, s[72:73]
	s_add_u32 s72, s72, 0x80
	s_addc_u32 s73, s73, 0
	s_add_i32 m0, s39, 0x4000
	s_nop 0
	global_load_lds_dwordx4 v184, s[68:69]
	s_add_i32 m0, s39, 0x4400
	s_nop 0
	global_load_lds_dwordx4 v185, s[68:69]
	s_add_u32 s68, s68, 0x80
	s_addc_u32 s69, s69, 0
	s_waitcnt lgkmcnt(0)
	s_waitcnt vmcnt(8)
	s_barrier
	s_setprio 1
	v_mfma_f32_16x16x32_bf16 v[24:27], v[0:3], v[152:155], v[24:27]
	v_mfma_f32_16x16x32_bf16 v[28:31], v[8:11], v[152:155], v[28:31]
	v_mfma_f32_16x16x32_bf16 v[32:35], v[0:3], v[160:163], v[32:35]
	v_mfma_f32_16x16x32_bf16 v[36:39], v[8:11], v[160:163], v[36:39]
	v_mfma_f32_16x16x32_bf16 v[40:43], v[0:3], v[168:171], v[40:43]
	v_mfma_f32_16x16x32_bf16 v[44:47], v[8:11], v[168:171], v[44:47]
	v_mfma_f32_16x16x32_bf16 v[48:51], v[0:3], v[176:179], v[48:51]
	v_mfma_f32_16x16x32_bf16 v[52:55], v[8:11], v[176:179], v[52:55]
	v_mfma_f32_16x16x32_bf16 v[24:27], v[4:7], v[156:159], v[24:27]
	v_mfma_f32_16x16x32_bf16 v[28:31], v[12:15], v[156:159], v[28:31]
	v_mfma_f32_16x16x32_bf16 v[32:35], v[4:7], v[164:167], v[32:35]
	v_mfma_f32_16x16x32_bf16 v[36:39], v[12:15], v[164:167], v[36:39]
	v_mfma_f32_16x16x32_bf16 v[40:43], v[4:7], v[172:175], v[40:43]
	v_mfma_f32_16x16x32_bf16 v[44:47], v[12:15], v[172:175], v[44:47]
	v_mfma_f32_16x16x32_bf16 v[48:51], v[4:7], v[180:183], v[48:51]
	v_mfma_f32_16x16x32_bf16 v[52:55], v[12:15], v[180:183], v[52:55]
	v_mfma_f32_16x16x32_bf16 v[56:59], v[196:199], v[152:155], v[56:59]
	v_mfma_f32_16x16x32_bf16 v[60:63], v[204:207], v[152:155], v[60:63]
	v_mfma_f32_16x16x32_bf16 v[64:67], v[196:199], v[160:163], v[64:67]
	v_mfma_f32_16x16x32_bf16 v[68:71], v[204:207], v[160:163], v[68:71]
	v_mfma_f32_16x16x32_bf16 v[72:75], v[196:199], v[168:171], v[72:75]
	v_mfma_f32_16x16x32_bf16 v[76:79], v[204:207], v[168:171], v[76:79]
	v_mfma_f32_16x16x32_bf16 v[80:83], v[196:199], v[176:179], v[80:83]
	v_mfma_f32_16x16x32_bf16 v[84:87], v[204:207], v[176:179], v[84:87]
	v_mfma_f32_16x16x32_bf16 v[56:59], v[200:203], v[156:159], v[56:59]
	v_mfma_f32_16x16x32_bf16 v[60:63], v[208:211], v[156:159], v[60:63]
	v_mfma_f32_16x16x32_bf16 v[64:67], v[200:203], v[164:167], v[64:67]
	v_mfma_f32_16x16x32_bf16 v[68:71], v[208:211], v[164:167], v[68:71]
	v_mfma_f32_16x16x32_bf16 v[72:75], v[200:203], v[172:175], v[72:75]
	v_mfma_f32_16x16x32_bf16 v[76:79], v[208:211], v[172:175], v[76:79]
	v_mfma_f32_16x16x32_bf16 v[80:83], v[200:203], v[180:183], v[80:83]
	v_mfma_f32_16x16x32_bf16 v[84:87], v[208:211], v[180:183], v[84:87]
	s_setprio 0
	s_barrier
	ds_read_b128 v[152:155], v186 offset:49168
	ds_read_b128 v[156:159], v187 offset:49168
	ds_read_b128 v[160:163], v186 offset:51216
	ds_read_b128 v[164:167], v187 offset:51216
	ds_read_b128 v[168:171], v186 offset:53264
	ds_read_b128 v[172:175], v187 offset:53264
	ds_read_b128 v[176:179], v186 offset:55312
	ds_read_b128 v[180:183], v187 offset:55312
	s_add_i32 m0, s39, 0x18000
	s_nop 0
	global_load_lds_dwordx4 v184, s[70:71]
	s_add_i32 m0, s39, 0x18400
	s_nop 0
	global_load_lds_dwordx4 v185, s[70:71]
	s_add_u32 s70, s70, 0x80
	s_addc_u32 s71, s71, 0
	s_add_i32 m0, s39, 0x8000
	s_nop 0
	global_load_lds_dwordx4 v184, s[66:67]
	s_add_i32 m0, s39, 0x8400
	s_nop 0
	global_load_lds_dwordx4 v185, s[66:67]
	s_add_u32 s66, s66, 0x80
	s_addc_u32 s67, s67, 0
	s_waitcnt lgkmcnt(0)
	s_waitcnt vmcnt(6)
	s_barrier
	s_setprio 1
	v_mfma_f32_16x16x32_bf16 v[88:91], v[0:3], v[152:155], v[88:91]
	v_mfma_f32_16x16x32_bf16 v[92:95], v[8:11], v[152:155], v[92:95]
	v_mfma_f32_16x16x32_bf16 v[96:99], v[0:3], v[160:163], v[96:99]
	v_mfma_f32_16x16x32_bf16 v[100:103], v[8:11], v[160:163], v[100:103]
	v_mfma_f32_16x16x32_bf16 v[104:107], v[0:3], v[168:171], v[104:107]
	v_mfma_f32_16x16x32_bf16 v[108:111], v[8:11], v[168:171], v[108:111]
	v_mfma_f32_16x16x32_bf16 v[112:115], v[0:3], v[176:179], v[112:115]
	v_mfma_f32_16x16x32_bf16 v[116:119], v[8:11], v[176:179], v[116:119]
	v_mfma_f32_16x16x32_bf16 v[88:91], v[4:7], v[156:159], v[88:91]
	v_mfma_f32_16x16x32_bf16 v[92:95], v[12:15], v[156:159], v[92:95]
	v_mfma_f32_16x16x32_bf16 v[96:99], v[4:7], v[164:167], v[96:99]
	v_mfma_f32_16x16x32_bf16 v[100:103], v[12:15], v[164:167], v[100:103]
	v_mfma_f32_16x16x32_bf16 v[104:107], v[4:7], v[172:175], v[104:107]
	v_mfma_f32_16x16x32_bf16 v[108:111], v[12:15], v[172:175], v[108:111]
	v_mfma_f32_16x16x32_bf16 v[112:115], v[4:7], v[180:183], v[112:115]
	v_mfma_f32_16x16x32_bf16 v[116:119], v[12:15], v[180:183], v[116:119]
	v_mfma_f32_16x16x32_bf16 v[120:123], v[196:199], v[152:155], v[120:123]
	v_mfma_f32_16x16x32_bf16 v[124:127], v[204:207], v[152:155], v[124:127]
	v_mfma_f32_16x16x32_bf16 v[128:131], v[196:199], v[160:163], v[128:131]
	v_mfma_f32_16x16x32_bf16 v[132:135], v[204:207], v[160:163], v[132:135]
	v_mfma_f32_16x16x32_bf16 v[136:139], v[196:199], v[168:171], v[136:139]
	v_mfma_f32_16x16x32_bf16 v[140:143], v[204:207], v[168:171], v[140:143]
	v_mfma_f32_16x16x32_bf16 v[144:147], v[196:199], v[176:179], v[144:147]
	v_mfma_f32_16x16x32_bf16 v[148:151], v[204:207], v[176:179], v[148:151]
	v_mfma_f32_16x16x32_bf16 v[120:123], v[200:203], v[156:159], v[120:123]
	v_mfma_f32_16x16x32_bf16 v[124:127], v[208:211], v[156:159], v[124:127]
	v_mfma_f32_16x16x32_bf16 v[128:131], v[200:203], v[164:167], v[128:131]
	v_mfma_f32_16x16x32_bf16 v[132:135], v[208:211], v[164:167], v[132:135]
	v_mfma_f32_16x16x32_bf16 v[136:139], v[200:203], v[172:175], v[136:139]
	v_mfma_f32_16x16x32_bf16 v[140:143], v[208:211], v[172:175], v[140:143]
	v_mfma_f32_16x16x32_bf16 v[144:147], v[200:203], v[180:183], v[144:147]
	v_mfma_f32_16x16x32_bf16 v[148:151], v[208:211], v[180:183], v[148:151]
	s_setprio 0
	s_barrier
; #define LAS __attribute__((address_space(3)))
; #define BAR() { __builtin_amdgcn_sched_barrier(0); __builtin_amdgcn_s_barrier(); asm volatile("" ::: "memory"); __builtin_amdgcn_sched_barrier(0); }
; DI void gemm_stream2(const bf16_t* __restrict__ A, int lda, const bf16_t* __restrict__ Bt, int ldb, int K, int m0, int n0, ...
;     ...
;     for (int kt = 0; kt < nk; ++kt) {
;         const bool pf = (kt + 2 < nk) || has_next, more = (kt + 1 < nk) || has_next;
;         const bf16_t* pa = (kt + 2 < nk) ? ga + (kt + 2) * 64 : gan + (kt + 2 - nk) * 64;
;         const bf16_t* pb = (kt + 2 < nk) ? gb + (kt + 2) * 64 : gbn + (kt + 2 - nk) * 64;
;         const int plda = (kt + 2 < nk) ? lda : ldan, pldb = (kt + 2 < nk) ? ldb : ldbn;
;         const int s2 = st >= 1 ? st - 1 : 2;
;         const LAS char* base = lds + st * 49152;
; #pragma unroll
;         for (int ks = 0; ks < 2; ++ks) {
;             const unsigned fo = ks ? fo1 : fo0;
;             bf16x8 af[4], bfr[4];
; #pragma unroll
;             for (int i = 0; i < 4; ++i) { af[i] = *(const LAS bf16x8*)(base + aoff + i * 2048 + fo); bfr[i] = *(const LAS bf16x8*)(base + boff + i * 2048 + fo); }
;             if (ks == 1 && more) { if (pf) asm volatile("s_waitcnt vmcnt(3)" ::: "memory"); else asm volatile("s_waitcnt vmcnt(0)" ::: "memory"); }
;             if (pf) { PIECE(s2, ks * 3 + 0); PIECE(s2, ks * 3 + 1); PIECE(s2, ks * 3 + 2); }
;             asm volatile("s_waitcnt lgkmcnt(0)" ::: "memory");
;             BAR();
;             __builtin_amdgcn_s_setprio(1);
; #pragma unroll
;             for (int mi = 0; mi < 4; ++mi)
; #pragma unroll
;                 for (int ni = 0; ni < 4; ++ni) acc[mi][ni] = __builtin_amdgcn_mfma_f32_16x16x32_bf16(bfr[ni], af[mi], acc[mi][ni], 0, 0, 0);
;             __builtin_amdgcn_s_setprio(0);
;             BAR();
;         }
;         st = st == 2 ? 0 : st + 1;
;     }
;     if (grp == 0) BAR();
	s_sub_u32 s0, s0, 1
	s_cmp_lg_u32 s0, 0
	s_cbranch_scc1 .Lgu_kloop
	s_cmp_lg_u32 s54, 0
	s_cbranch_scc1 .Lgu_epi
	ds_read_b128 v[0:3], v188 offset:16
	ds_read_b128 v[4:7], v189 offset:16
	ds_read_b128 v[8:11], v188 offset:2064
	ds_read_b128 v[12:15], v189 offset:2064
	ds_read_b128 v[196:199], v188 offset:16400
	ds_read_b128 v[200:203], v189 offset:16400
	ds_read_b128 v[204:207], v188 offset:18448
	ds_read_b128 v[208:211], v189 offset:18448
	ds_read_b128 v[152:155], v186 offset:16
	ds_read_b128 v[156:159], v187 offset:16
	ds_read_b128 v[160:163], v186 offset:2064
	ds_read_b128 v[164:167], v187 offset:2064
	ds_read_b128 v[168:171], v186 offset:4112
	ds_read_b128 v[172:175], v187 offset:4112
	ds_read_b128 v[176:179], v186 offset:6160
	ds_read_b128 v[180:183], v187 offset:6160
	s_add_i32 m0, s39, 0x1c000
	s_nop 0
	global_load_lds_dwordx4 v184, s[72:73]
	s_add_i32 m0, s39, 0x1c400
	s_nop 0
	global_load_lds_dwordx4 v185, s[72:73]
	s_add_u32 s72, s72, 0x80
	s_addc_u32 s73, s73, 0
	s_add_i32 m0, s39, 0xc000
	s_nop 0
	global_load_lds_dwordx4 v184, s[68:69]
	s_add_i32 m0, s39, 0xc400
	s_nop 0
	global_load_lds_dwordx4 v185, s[68:69]
	s_add_u32 s68, s68, 0x80
	s_addc_u32 s69, s69, 0
	s_waitcnt lgkmcnt(0)
	s_waitcnt vmcnt(8)
	s_barrier
	s_setprio 1
	v_mfma_f32_16x16x32_bf16 v[24:27], v[0:3], v[152:155], v[24:27]
	v_mfma_f32_16x16x32_bf16 v[28:31], v[8:11], v[152:155], v[28:31]
	v_mfma_f32_16x16x32_bf16 v[32:35], v[0:3], v[160:163], v[32:35]
	v_mfma_f32_16x16x32_bf16 v[36:39], v[8:11], v[160:163], v[36:39]
	v_mfma_f32_16x16x32_bf16 v[40:43], v[0:3], v[168:171], v[40:43]
	v_mfma_f32_16x16x32_bf16 v[44:47], v[8:11], v[168:171], v[44:47]
	v_mfma_f32_16x16x32_bf16 v[48:51], v[0:3], v[176:179], v[48:51]
	v_mfma_f32_16x16x32_bf16 v[52:55], v[8:11], v[176:179], v[52:55]
	v_mfma_f32_16x16x32_bf16 v[24:27], v[4:7], v[156:159], v[24:27]
	v_mfma_f32_16x16x32_bf16 v[28:31], v[12:15], v[156:159], v[28:31]
	v_mfma_f32_16x16x32_bf16 v[32:35], v[4:7], v[164:167], v[32:35]
	v_mfma_f32_16x16x32_bf16 v[36:39], v[12:15], v[164:167], v[36:39]
	v_mfma_f32_16x16x32_bf16 v[40:43], v[4:7], v[172:175], v[40:43]
	v_mfma_f32_16x16x32_bf16 v[44:47], v[12:15], v[172:175], v[44:47]
	v_mfma_f32_16x16x32_bf16 v[48:51], v[4:7], v[180:183], v[48:51]
	v_mfma_f32_16x16x32_bf16 v[52:55], v[12:15], v[180:183], v[52:55]
	v_mfma_f32_16x16x32_bf16 v[56:59], v[196:199], v[152:155], v[56:59]
	v_mfma_f32_16x16x32_bf16 v[60:63], v[204:207], v[152:155], v[60:63]
	v_mfma_f32_16x16x32_bf16 v[64:67], v[196:199], v[160:163], v[64:67]
	v_mfma_f32_16x16x32_bf16 v[68:71], v[204:207], v[160:163], v[68:71]
	v_mfma_f32_16x16x32_bf16 v[72:75], v[196:199], v[168:171], v[72:75]
	v_mfma_f32_16x16x32_bf16 v[76:79], v[204:207], v[168:171], v[76:79]
	v_mfma_f32_16x16x32_bf16 v[80:83], v[196:199], v[176:179], v[80:83]
	v_mfma_f32_16x16x32_bf16 v[84:87], v[204:207], v[176:179], v[84:87]
	v_mfma_f32_16x16x32_bf16 v[56:59], v[200:203], v[156:159], v[56:59]
	v_mfma_f32_16x16x32_bf16 v[60:63], v[208:211], v[156:159], v[60:63]
	v_mfma_f32_16x16x32_bf16 v[64:67], v[200:203], v[164:167], v[64:67]
	v_mfma_f32_16x16x32_bf16 v[68:71], v[208:211], v[164:167], v[68:71]
	v_mfma_f32_16x16x32_bf16 v[72:75], v[200:203], v[172:175], v[72:75]
	v_mfma_f32_16x16x32_bf16 v[76:79], v[208:211], v[172:175], v[76:79]
	v_mfma_f32_16x16x32_bf16 v[80:83], v[200:203], v[180:183], v[80:83]
	v_mfma_f32_16x16x32_bf16 v[84:87], v[208:211], v[180:183], v[84:87]
	s_setprio 0
	s_barrier
	ds_read_b128 v[152:155], v186 offset:16400
	ds_read_b128 v[156:159], v187 offset:16400
	ds_read_b128 v[160:163], v186 offset:18448
	ds_read_b128 v[164:167], v187 offset:18448
	ds_read_b128 v[168:171], v186 offset:20496
	ds_read_b128 v[172:175], v187 offset:20496
	ds_read_b128 v[176:179], v186 offset:22544
	ds_read_b128 v[180:183], v187 offset:22544
	s_waitcnt lgkmcnt(0)
	s_waitcnt vmcnt(2)
	s_barrier
	s_setprio 1
	v_mfma_f32_16x16x32_bf16 v[88:91], v[0:3], v[152:155], v[88:91]
	v_mfma_f32_16x16x32_bf16 v[92:95], v[8:11], v[152:155], v[92:95]
	v_mfma_f32_16x16x32_bf16 v[96:99], v[0:3], v[160:163], v[96:99]
	v_mfma_f32_16x16x32_bf16 v[100:103], v[8:11], v[160:163], v[100:103]
	v_mfma_f32_16x16x32_bf16 v[104:107], v[0:3], v[168:171], v[104:107]
	v_mfma_f32_16x16x32_bf16 v[108:111], v[8:11], v[168:171], v[108:111]
	v_mfma_f32_16x16x32_bf16 v[112:115], v[0:3], v[176:179], v[112:115]
	v_mfma_f32_16x16x32_bf16 v[116:119], v[8:11], v[176:179], v[116:119]
	v_mfma_f32_16x16x32_bf16 v[88:91], v[4:7], v[156:159], v[88:91]
	v_mfma_f32_16x16x32_bf16 v[92:95], v[12:15], v[156:159], v[92:95]
	v_mfma_f32_16x16x32_bf16 v[96:99], v[4:7], v[164:167], v[96:99]
	v_mfma_f32_16x16x32_bf16 v[100:103], v[12:15], v[164:167], v[100:103]
	v_mfma_f32_16x16x32_bf16 v[104:107], v[4:7], v[172:175], v[104:107]
	v_mfma_f32_16x16x32_bf16 v[108:111], v[12:15], v[172:175], v[108:111]
	v_mfma_f32_16x16x32_bf16 v[112:115], v[4:7], v[180:183], v[112:115]
	v_mfma_f32_16x16x32_bf16 v[116:119], v[12:15], v[180:183], v[116:119]
	v_mfma_f32_16x16x32_bf16 v[120:123], v[196:199], v[152:155], v[120:123]
	v_mfma_f32_16x16x32_bf16 v[124:127], v[204:207], v[152:155], v[124:127]
	v_mfma_f32_16x16x32_bf16 v[128:131], v[196:199], v[160:163], v[128:131]
	v_mfma_f32_16x16x32_bf16 v[132:135], v[204:207], v[160:163], v[132:135]
	v_mfma_f32_16x16x32_bf16 v[136:139], v[196:199], v[168:171], v[136:139]
	v_mfma_f32_16x16x32_bf16 v[140:143], v[204:207], v[168:171], v[140:143]
	v_mfma_f32_16x16x32_bf16 v[144:147], v[196:199], v[176:179], v[144:147]
	v_mfma_f32_16x16x32_bf16 v[148:151], v[204:207], v[176:179], v[148:151]
	v_mfma_f32_16x16x32_bf16 v[120:123], v[200:203], v[156:159], v[120:123]
	v_mfma_f32_16x16x32_bf16 v[124:127], v[208:211], v[156:159], v[124:127]
	v_mfma_f32_16x16x32_bf16 v[128:131], v[200:203], v[164:167], v[128:131]
	v_mfma_f32_16x16x32_bf16 v[132:135], v[208:211], v[164:167], v[132:135]
	v_mfma_f32_16x16x32_bf16 v[136:139], v[200:203], v[172:175], v[136:139]
	v_mfma_f32_16x16x32_bf16 v[140:143], v[208:211], v[172:175], v[140:143]
	v_mfma_f32_16x16x32_bf16 v[144:147], v[200:203], v[180:183], v[144:147]
	v_mfma_f32_16x16x32_bf16 v[148:151], v[208:211], v[180:183], v[148:151]
	s_setprio 0
	s_barrier
; #define LAS __attribute__((address_space(3)))
; #define BAR() { __builtin_amdgcn_sched_barrier(0); __builtin_amdgcn_s_barrier(); asm volatile("" ::: "memory"); __builtin_amdgcn_sched_barrier(0); }
; DI void gemm_stream2(const bf16_t* __restrict__ A, int lda, const bf16_t* __restrict__ Bt, int ldb, int K, int m0, int n0, ...
;     ...
;         const int s2 = st >= 1 ? st - 1 : 2;
;         const LAS char* base = lds + st * 49152;
; #pragma unroll
;         for (int ks = 0; ks < 2; ++ks) {
;             const unsigned fo = ks ? fo1 : fo0;
;             bf16x8 af[4], bfr[4];
; #pragma unroll
;             for (int i = 0; i < 4; ++i) { af[i] = *(const LAS bf16x8*)(base + aoff + i * 2048 + fo); bfr[i] = *(const LAS bf16x8*)(base + boff + i * 2048 + fo); }
;             if (ks == 1 && more) { if (pf) asm volatile("s_waitcnt vmcnt(3)" ::: "memory"); else asm volatile("s_waitcnt vmcnt(0)" ::: "memory"); }
;             if (pf) { PIECE(s2, ks * 3 + 0); PIECE(s2, ks * 3 + 1); PIECE(s2, ks * 3 + 2); }
;             asm volatile("s_waitcnt lgkmcnt(0)" ::: "memory");
;             BAR();
;             __builtin_amdgcn_s_setprio(1);
; #pragma unroll
;             for (int mi = 0; mi < 4; ++mi)
; #pragma unroll
;                 for (int ni = 0; ni < 4; ++ni) acc[mi][ni] = __builtin_amdgcn_mfma_f32_16x16x32_bf16(bfr[ni], af[mi], acc[mi][ni], 0, 0, 0);
;             __builtin_amdgcn_s_setprio(0);
;             BAR();
;         }
;         st = st == 2 ? 0 : st + 1;
;     }
;     if (grp == 0) BAR();
	ds_read_b128 v[0:3], v188 offset:32784
	ds_read_b128 v[4:7], v189 offset:32784
	ds_read_b128 v[8:11], v188 offset:34832
	ds_read_b128 v[12:15], v189 offset:34832
	ds_read_b128 v[196:199], v188 offset:49168
	ds_read_b128 v[200:203], v189 offset:49168
	ds_read_b128 v[204:207], v188 offset:51216
	ds_read_b128 v[208:211], v189 offset:51216
	ds_read_b128 v[152:155], v186 offset:32784
	ds_read_b128 v[156:159], v187 offset:32784
	ds_read_b128 v[160:163], v186 offset:34832
	ds_read_b128 v[164:167], v187 offset:34832
	ds_read_b128 v[168:171], v186 offset:36880
	ds_read_b128 v[172:175], v187 offset:36880
	ds_read_b128 v[176:179], v186 offset:38928
	ds_read_b128 v[180:183], v187 offset:38928
	s_waitcnt lgkmcnt(0)
	s_waitcnt vmcnt(0)
	s_barrier
	s_setprio 1
	v_mfma_f32_16x16x32_bf16 v[24:27], v[0:3], v[152:155], v[24:27]
	v_mfma_f32_16x16x32_bf16 v[28:31], v[8:11], v[152:155], v[28:31]
	v_mfma_f32_16x16x32_bf16 v[32:35], v[0:3], v[160:163], v[32:35]
	v_mfma_f32_16x16x32_bf16 v[36:39], v[8:11], v[160:163], v[36:39]
	v_mfma_f32_16x16x32_bf16 v[40:43], v[0:3], v[168:171], v[40:43]
	v_mfma_f32_16x16x32_bf16 v[44:47], v[8:11], v[168:171], v[44:47]
	v_mfma_f32_16x16x32_bf16 v[48:51], v[0:3], v[176:179], v[48:51]
	v_mfma_f32_16x16x32_bf16 v[52:55], v[8:11], v[176:179], v[52:55]
	v_mfma_f32_16x16x32_bf16 v[24:27], v[4:7], v[156:159], v[24:27]
	v_mfma_f32_16x16x32_bf16 v[28:31], v[12:15], v[156:159], v[28:31]
	v_mfma_f32_16x16x32_bf16 v[32:35], v[4:7], v[164:167], v[32:35]
	v_mfma_f32_16x16x32_bf16 v[36:39], v[12:15], v[164:167], v[36:39]
	v_mfma_f32_16x16x32_bf16 v[40:43], v[4:7], v[172:175], v[40:43]
	v_mfma_f32_16x16x32_bf16 v[44:47], v[12:15], v[172:175], v[44:47]
	v_mfma_f32_16x16x32_bf16 v[48:51], v[4:7], v[180:183], v[48:51]
	v_mfma_f32_16x16x32_bf16 v[52:55], v[12:15], v[180:183], v[52:55]
	v_mfma_f32_16x16x32_bf16 v[56:59], v[196:199], v[152:155], v[56:59]
	v_mfma_f32_16x16x32_bf16 v[60:63], v[204:207], v[152:155], v[60:63]
	v_mfma_f32_16x16x32_bf16 v[64:67], v[196:199], v[160:163], v[64:67]
	v_mfma_f32_16x16x32_bf16 v[68:71], v[204:207], v[160:163], v[68:71]
	v_mfma_f32_16x16x32_bf16 v[72:75], v[196:199], v[168:171], v[72:75]
	v_mfma_f32_16x16x32_bf16 v[76:79], v[204:207], v[168:171], v[76:79]
	v_mfma_f32_16x16x32_bf16 v[80:83], v[196:199], v[176:179], v[80:83]
	v_mfma_f32_16x16x32_bf16 v[84:87], v[204:207], v[176:179], v[84:87]
	v_mfma_f32_16x16x32_bf16 v[56:59], v[200:203], v[156:159], v[56:59]
	v_mfma_f32_16x16x32_bf16 v[60:63], v[208:211], v[156:159], v[60:63]
	v_mfma_f32_16x16x32_bf16 v[64:67], v[200:203], v[164:167], v[64:67]
	v_mfma_f32_16x16x32_bf16 v[68:71], v[208:211], v[164:167], v[68:71]
	v_mfma_f32_16x16x32_bf16 v[72:75], v[200:203], v[172:175], v[72:75]
	v_mfma_f32_16x16x32_bf16 v[76:79], v[208:211], v[172:175], v[76:79]
	v_mfma_f32_16x16x32_bf16 v[80:83], v[200:203], v[180:183], v[80:83]
	v_mfma_f32_16x16x32_bf16 v[84:87], v[208:211], v[180:183], v[84:87]
	s_setprio 0
	s_barrier
	ds_read_b128 v[152:155], v186 offset:49168
	ds_read_b128 v[156:159], v187 offset:49168
	ds_read_b128 v[160:163], v186 offset:51216
	ds_read_b128 v[164:167], v187 offset:51216
	ds_read_b128 v[168:171], v186 offset:53264
	ds_read_b128 v[172:175], v187 offset:53264
	ds_read_b128 v[176:179], v186 offset:55312
	ds_read_b128 v[180:183], v187 offset:55312
	s_waitcnt lgkmcnt(0)
	s_barrier
	s_setprio 1
	v_mfma_f32_16x16x32_bf16 v[88:91], v[0:3], v[152:155], v[88:91]
	v_mfma_f32_16x16x32_bf16 v[92:95], v[8:11], v[152:155], v[92:95]
	v_mfma_f32_16x16x32_bf16 v[96:99], v[0:3], v[160:163], v[96:99]
	v_mfma_f32_16x16x32_bf16 v[100:103], v[8:11], v[160:163], v[100:103]
	v_mfma_f32_16x16x32_bf16 v[104:107], v[0:3], v[168:171], v[104:107]
	v_mfma_f32_16x16x32_bf16 v[108:111], v[8:11], v[168:171], v[108:111]
	v_mfma_f32_16x16x32_bf16 v[112:115], v[0:3], v[176:179], v[112:115]
	v_mfma_f32_16x16x32_bf16 v[116:119], v[8:11], v[176:179], v[116:119]
	v_mfma_f32_16x16x32_bf16 v[88:91], v[4:7], v[156:159], v[88:91]
	v_mfma_f32_16x16x32_bf16 v[92:95], v[12:15], v[156:159], v[92:95]
	v_mfma_f32_16x16x32_bf16 v[96:99], v[4:7], v[164:167], v[96:99]
	v_mfma_f32_16x16x32_bf16 v[100:103], v[12:15], v[164:167], v[100:103]
	v_mfma_f32_16x16x32_bf16 v[104:107], v[4:7], v[172:175], v[104:107]
	v_mfma_f32_16x16x32_bf16 v[108:111], v[12:15], v[172:175], v[108:111]
	v_mfma_f32_16x16x32_bf16 v[112:115], v[4:7], v[180:183], v[112:115]
	v_mfma_f32_16x16x32_bf16 v[116:119], v[12:15], v[180:183], v[116:119]
	v_mfma_f32_16x16x32_bf16 v[120:123], v[196:199], v[152:155], v[120:123]
	v_mfma_f32_16x16x32_bf16 v[124:127], v[204:207], v[152:155], v[124:127]
	v_mfma_f32_16x16x32_bf16 v[128:131], v[196:199], v[160:163], v[128:131]
	v_mfma_f32_16x16x32_bf16 v[132:135], v[204:207], v[160:163], v[132:135]
	v_mfma_f32_16x16x32_bf16 v[136:139], v[196:199], v[168:171], v[136:139]
	v_mfma_f32_16x16x32_bf16 v[140:143], v[204:207], v[168:171], v[140:143]
	v_mfma_f32_16x16x32_bf16 v[144:147], v[196:199], v[176:179], v[144:147]
	v_mfma_f32_16x16x32_bf16 v[148:151], v[204:207], v[176:179], v[148:151]
	v_mfma_f32_16x16x32_bf16 v[120:123], v[200:203], v[156:159], v[120:123]
	v_mfma_f32_16x16x32_bf16 v[124:127], v[208:211], v[156:159], v[124:127]
	v_mfma_f32_16x16x32_bf16 v[128:131], v[200:203], v[164:167], v[128:131]
	v_mfma_f32_16x16x32_bf16 v[132:135], v[208:211], v[164:167], v[132:135]
	v_mfma_f32_16x16x32_bf16 v[136:139], v[200:203], v[172:175], v[136:139]
	v_mfma_f32_16x16x32_bf16 v[140:143], v[208:211], v[172:175], v[140:143]
	v_mfma_f32_16x16x32_bf16 v[144:147], v[200:203], v[180:183], v[144:147]
	v_mfma_f32_16x16x32_bf16 v[148:151], v[208:211], v[180:183], v[148:151]
	s_setprio 0
	s_barrier
	s_cmp_lg_u32 s33, 0
	s_cbranch_scc1 .Lgu_epi
	s_barrier

; #define BAR() { __builtin_amdgcn_sched_barrier(0); __builtin_amdgcn_s_barrier(); asm volatile("" ::: "memory"); __builtin_amdgcn_sched_barrier(0); }
; DI void gemm_stream2(const bf16_t* __restrict__ A, int lda, const bf16_t* __restrict__ Bt, int ldb, int K, int m0, int n0, ...
;     ...
;     const int wave = __builtin_amdgcn_readfirstlane(tid >> 6), lane = tid & 63, wm = wave >> 1, wn = wave & 1, r = lane & 15, q = lane >> 4;
;     const int sc0 = ((lane & 7) ^ (lane >> 4)) * 8, sc1 = ((lane & 7) ^ (4 | (lane >> 4))) * 8;
;     const bf16_t* ga = A + (size_t)(m0 + wave * 32 + (lane >> 3)) * lda;
;     const bf16_t* gb = Bt + (size_t)(n0 + wave * 16 + (lane >> 3)) * ldb;
;     const bf16_t* gan = An + (size_t)(m0n + wave * 32 + (lane >> 3)) * ldan;
;     const bf16_t* gbn = Btn + (size_t)(n0n + wave * 16 + (lane >> 3)) * ldbn;
;     const unsigned wa = (unsigned)wave * 4096u, wbb = 32768u + (unsigned)wave * 2048u;
;     ...
;     const int sw = r >> 1;
;     const unsigned fo0 = (unsigned)(r * 128 + ((q ^ sw) << 4)), fo1 = (unsigned)(r * 128 + (((q ^ sw) ^ 4) << 4));
;     const unsigned aoff = (unsigned)(wm * 64) * 128u, boff = 32768u + (unsigned)(wn * 64) * 128u;
;     const int nk = K / 64;
;     const int grp = wave >> 2;
;     ...
;     int st = rg.st;
;     if (!rg.primed) {
;         const int s1p = st == 2 ? 0 : st + 1;
;         BAR();
;         STAGE(st, 0);
;         STAGE(s1p, 1);
;         asm volatile("s_waitcnt vmcnt(6)" ::: "memory");
;         BAR();
;     }
;     if (grp == 1) BAR();
; DI void gemm_y(const Params& p, const bf16_t* A, int lda, size_t woff, int K, int kper, int bid, int nb, char* smem, const int tid) {
;     ...
;     for (; have; tm = tm2, tn = tn2) {
;         have = ti.next(tm2, tn2);
;         const int m0 = tm * 256, n0 = tn * 128;
;         f32x4 acc[4][4]; zero_acc(acc);
;         gemm_stream(A, lda, Bt, K, K, m0, n0, have, tm2 * 256, tn2 * 128, smem, acc, tid, rg);
.Lgyd_lanes:
	v_and_b32_e32 v190, 63, v193
	v_and_b32_e32 v191, 15, v190
	v_lshrrev_b32_e32 v17, 4, v190
	v_lshrrev_b32_e32 v18, 3, v190
	v_and_b32_e32 v19, 7, v190
	v_xor_b32_e32 v195, v19, v17
	v_lshlrev_b32_e32 v195, 4, v195
	s_mov_b32 s1, 0x1600
	v_mad_u32_u24 v184, v18, s1, v195
	v_or_b32_e32 v195, 4, v17
	v_xor_b32_e32 v195, v19, v195
	v_lshlrev_b32_e32 v195, 4, v195
	v_add_u32_e32 v227, 8, v18
	v_mad_u32_u24 v185, v227, s1, v195
	v_lshrrev_b32_e32 v195, 1, v191
	v_xor_b32_e32 v195, v17, v195
	v_lshlrev_b32_e32 v195, 4, v195
	s_lshl_b32 s1, s33, 6
	v_add_u32_e32 v227, s1, v191
	v_lshl_add_u32 v186, v227, 7, v195
	v_xor_b32_e32 v187, 64, v186
	v_lshlrev_b32_e32 v228, 11, v227
	s_lshl_b32 s1, s36, 5
	v_add_u32_e32 v227, s1, v191
	v_lshl_add_u32 v188, v227, 7, v195
	v_add_u32_e32 v188, 0x10000, v188
	v_xor_b32_e32 v189, 64, v188
	s_lshl_b32 s1, s36, 6
	v_lshl_add_u32 v229, v17, 3, s1
	v_add_u32_e32 v237, v228, v229
	v_and_b32_e32 v227, 1, v17
	v_mul_u32_u24_e32 v227, 0x7ff8, v227
	v_add_u32_e32 v236, v237, v227
	s_add_i32 m0, s39, 0x10000
	s_nop 0
	global_load_lds_dwordx4 v184, s[70:71]
	s_add_i32 m0, s39, 0x10400
	s_nop 0
	global_load_lds_dwordx4 v185, s[70:71]
	s_add_u32 s70, s70, 0x80
	s_addc_u32 s71, s71, 0
	s_add_i32 m0, s39, 0x0
	s_nop 0
	global_load_lds_dwordx4 v184, s[66:67]
	s_add_i32 m0, s39, 0x400
	s_nop 0
	global_load_lds_dwordx4 v185, s[66:67]
	s_add_u32 s66, s66, 0x80
	s_addc_u32 s67, s67, 0
	s_add_i32 m0, s39, 0x14000
	s_nop 0
	global_load_lds_dwordx4 v184, s[72:73]
	s_add_i32 m0, s39, 0x14400
	s_nop 0
	global_load_lds_dwordx4 v185, s[72:73]
	s_add_u32 s72, s72, 0x80
	s_addc_u32 s73, s73, 0
	s_add_i32 m0, s39, 0x4000
	s_nop 0
	global_load_lds_dwordx4 v184, s[68:69]
	s_add_i32 m0, s39, 0x4400
	s_nop 0
	global_load_lds_dwordx4 v185, s[68:69]
	s_add_u32 s68, s68, 0x80
	s_addc_u32 s69, s69, 0
	s_add_i32 m0, s39, 0x18000
	s_nop 0
	global_load_lds_dwordx4 v184, s[70:71]
	s_add_i32 m0, s39, 0x18400
	s_nop 0
	global_load_lds_dwordx4 v185, s[70:71]
	s_add_u32 s70, s70, 0x80
	s_addc_u32 s71, s71, 0
	s_add_i32 m0, s39, 0x8000
	s_nop 0
	global_load_lds_dwordx4 v184, s[66:67]
	s_add_i32 m0, s39, 0x8400
	s_nop 0
	global_load_lds_dwordx4 v185, s[66:67]
	s_add_u32 s66, s66, 0x80
	s_addc_u32 s67, s67, 0
	s_waitcnt vmcnt(6)
	s_barrier
	s_cmp_eq_u32 s33, 0
	s_cbranch_scc1 .Lgyd_lead
	s_barrier

; #define LAS __attribute__((address_space(3)))
; #define BAR() { __builtin_amdgcn_sched_barrier(0); __builtin_amdgcn_s_barrier(); asm volatile("" ::: "memory"); __builtin_amdgcn_sched_barrier(0); }
; DI void gemm_stream2(const bf16_t* __restrict__ A, int lda, const bf16_t* __restrict__ Bt, int ldb, int K, int m0, int n0, ...
;     ...
;     for (int kt = 0; kt < nk; ++kt) {
;         const bool pf = (kt + 2 < nk) || has_next, more = (kt + 1 < nk) || has_next;
;         const bf16_t* pa = (kt + 2 < nk) ? ga + (kt + 2) * 64 : gan + (kt + 2 - nk) * 64;
;         const bf16_t* pb = (kt + 2 < nk) ? gb + (kt + 2) * 64 : gbn + (kt + 2 - nk) * 64;
;         const int plda = (kt + 2 < nk) ? lda : ldan, pldb = (kt + 2 < nk) ? ldb : ldbn;
;         const int s2 = st >= 1 ? st - 1 : 2;
;         const LAS char* base = lds + st * 49152;
; #pragma unroll
;         for (int ks = 0; ks < 2; ++ks) {
;             const unsigned fo = ks ? fo1 : fo0;
;             bf16x8 af[4], bfr[4];
; #pragma unroll
;             for (int i = 0; i < 4; ++i) { af[i] = *(const LAS bf16x8*)(base + aoff + i * 2048 + fo); bfr[i] = *(const LAS bf16x8*)(base + boff + i * 2048 + fo); }
;             if (ks == 1 && more) { if (pf) asm volatile("s_waitcnt vmcnt(3)" ::: "memory"); else asm volatile("s_waitcnt vmcnt(0)" ::: "memory"); }
;             if (pf) { PIECE(s2, ks * 3 + 0); PIECE(s2, ks * 3 + 1); PIECE(s2, ks * 3 + 2); }
;             asm volatile("s_waitcnt lgkmcnt(0)" ::: "memory");
;             BAR();
;             __builtin_amdgcn_s_setprio(1);
; #pragma unroll
;             for (int mi = 0; mi < 4; ++mi)
; #pragma unroll
;                 for (int ni = 0; ni < 4; ++ni) acc[mi][ni] = __builtin_amdgcn_mfma_f32_16x16x32_bf16(bfr[ni], af[mi], acc[mi][ni], 0, 0, 0);
;             __builtin_amdgcn_s_setprio(0);
;             BAR();
;         }
.Lgyd_nosw2:
	s_add_i32 m0, s39, 0x14000
	s_nop 0
	global_load_lds_dwordx4 v184, s[72:73]
	s_add_i32 m0, s39, 0x14400
	s_nop 0
	global_load_lds_dwordx4 v185, s[72:73]
	s_add_u32 s72, s72, 0x80
	s_addc_u32 s73, s73, 0
	s_add_i32 m0, s39, 0x4000
	s_nop 0
	global_load_lds_dwordx4 v184, s[68:69]
	s_add_i32 m0, s39, 0x4400
	s_nop 0
	global_load_lds_dwordx4 v185, s[68:69]
	s_add_u32 s68, s68, 0x80
	s_addc_u32 s69, s69, 0
	s_waitcnt lgkmcnt(0)
	s_waitcnt vmcnt(8)
	s_barrier
	s_setprio 1
	v_mfma_f32_16x16x32_bf16 v[24:27], v[0:3], v[152:155], v[24:27]
	v_mfma_f32_16x16x32_bf16 v[28:31], v[8:11], v[152:155], v[28:31]
	v_mfma_f32_16x16x32_bf16 v[32:35], v[0:3], v[160:163], v[32:35]
	v_mfma_f32_16x16x32_bf16 v[36:39], v[8:11], v[160:163], v[36:39]
	v_mfma_f32_16x16x32_bf16 v[40:43], v[0:3], v[168:171], v[40:43]
	v_mfma_f32_16x16x32_bf16 v[44:47], v[8:11], v[168:171], v[44:47]
	v_mfma_f32_16x16x32_bf16 v[48:51], v[0:3], v[176:179], v[48:51]
	v_mfma_f32_16x16x32_bf16 v[52:55], v[8:11], v[176:179], v[52:55]
	v_mfma_f32_16x16x32_bf16 v[24:27], v[4:7], v[156:159], v[24:27]
	v_mfma_f32_16x16x32_bf16 v[28:31], v[12:15], v[156:159], v[28:31]
	v_mfma_f32_16x16x32_bf16 v[32:35], v[4:7], v[164:167], v[32:35]
	v_mfma_f32_16x16x32_bf16 v[36:39], v[12:15], v[164:167], v[36:39]
	v_mfma_f32_16x16x32_bf16 v[40:43], v[4:7], v[172:175], v[40:43]
	v_mfma_f32_16x16x32_bf16 v[44:47], v[12:15], v[172:175], v[44:47]
	v_mfma_f32_16x16x32_bf16 v[48:51], v[4:7], v[180:183], v[48:51]
	v_mfma_f32_16x16x32_bf16 v[52:55], v[12:15], v[180:183], v[52:55]
	v_mfma_f32_16x16x32_bf16 v[56:59], v[196:199], v[152:155], v[56:59]
	v_mfma_f32_16x16x32_bf16 v[60:63], v[204:207], v[152:155], v[60:63]
	v_mfma_f32_16x16x32_bf16 v[64:67], v[196:199], v[160:163], v[64:67]
	v_mfma_f32_16x16x32_bf16 v[68:71], v[204:207], v[160:163], v[68:71]
	v_mfma_f32_16x16x32_bf16 v[72:75], v[196:199], v[168:171], v[72:75]
	v_mfma_f32_16x16x32_bf16 v[76:79], v[204:207], v[168:171], v[76:79]
	v_mfma_f32_16x16x32_bf16 v[80:83], v[196:199], v[176:179], v[80:83]
	v_mfma_f32_16x16x32_bf16 v[84:87], v[204:207], v[176:179], v[84:87]
	v_mfma_f32_16x16x32_bf16 v[56:59], v[200:203], v[156:159], v[56:59]
	v_mfma_f32_16x16x32_bf16 v[60:63], v[208:211], v[156:159], v[60:63]
	v_mfma_f32_16x16x32_bf16 v[64:67], v[200:203], v[164:167], v[64:67]
	v_mfma_f32_16x16x32_bf16 v[68:71], v[208:211], v[164:167], v[68:71]
	v_mfma_f32_16x16x32_bf16 v[72:75], v[200:203], v[172:175], v[72:75]
	v_mfma_f32_16x16x32_bf16 v[76:79], v[208:211], v[172:175], v[76:79]
	v_mfma_f32_16x16x32_bf16 v[80:83], v[200:203], v[180:183], v[80:83]
	v_mfma_f32_16x16x32_bf16 v[84:87], v[208:211], v[180:183], v[84:87]
	s_setprio 0
	s_barrier
	ds_read_b128 v[152:155], v186 offset:49168
	ds_read_b128 v[156:159], v187 offset:49168
	ds_read_b128 v[160:163], v186 offset:51216
	ds_read_b128 v[164:167], v187 offset:51216
	ds_read_b128 v[168:171], v186 offset:53264
	ds_read_b128 v[172:175], v187 offset:53264
	ds_read_b128 v[176:179], v186 offset:55312
	ds_read_b128 v[180:183], v187 offset:55312
	s_add_i32 m0, s39, 0x18000
	s_nop 0
	global_load_lds_dwordx4 v184, s[70:71]
	s_add_i32 m0, s39, 0x18400
	s_nop 0
	global_load_lds_dwordx4 v185, s[70:71]
	s_add_u32 s70, s70, 0x80
	s_addc_u32 s71, s71, 0
	s_add_i32 m0, s39, 0x8000
	s_nop 0
	global_load_lds_dwordx4 v184, s[66:67]
	s_add_i32 m0, s39, 0x8400
	s_nop 0
	global_load_lds_dwordx4 v185, s[66:67]
	s_add_u32 s66, s66, 0x80
	s_addc_u32 s67, s67, 0
	s_waitcnt lgkmcnt(0)
	s_waitcnt vmcnt(6)
	s_barrier
	s_setprio 1
	v_mfma_f32_16x16x32_bf16 v[88:91], v[0:3], v[152:155], v[88:91]
	v_mfma_f32_16x16x32_bf16 v[92:95], v[8:11], v[152:155], v[92:95]
	v_mfma_f32_16x16x32_bf16 v[96:99], v[0:3], v[160:163], v[96:99]
	v_mfma_f32_16x16x32_bf16 v[100:103], v[8:11], v[160:163], v[100:103]
	v_mfma_f32_16x16x32_bf16 v[104:107], v[0:3], v[168:171], v[104:107]
	v_mfma_f32_16x16x32_bf16 v[108:111], v[8:11], v[168:171], v[108:111]
	v_mfma_f32_16x16x32_bf16 v[112:115], v[0:3], v[176:179], v[112:115]
	v_mfma_f32_16x16x32_bf16 v[116:119], v[8:11], v[176:179], v[116:119]
	v_mfma_f32_16x16x32_bf16 v[88:91], v[4:7], v[156:159], v[88:91]
	v_mfma_f32_16x16x32_bf16 v[92:95], v[12:15], v[156:159], v[92:95]
	v_mfma_f32_16x16x32_bf16 v[96:99], v[4:7], v[164:167], v[96:99]
	v_mfma_f32_16x16x32_bf16 v[100:103], v[12:15], v[164:167], v[100:103]
	v_mfma_f32_16x16x32_bf16 v[104:107], v[4:7], v[172:175], v[104:107]
	v_mfma_f32_16x16x32_bf16 v[108:111], v[12:15], v[172:175], v[108:111]
	v_mfma_f32_16x16x32_bf16 v[112:115], v[4:7], v[180:183], v[112:115]
	v_mfma_f32_16x16x32_bf16 v[116:119], v[12:15], v[180:183], v[116:119]
	v_mfma_f32_16x16x32_bf16 v[120:123], v[196:199], v[152:155], v[120:123]
	v_mfma_f32_16x16x32_bf16 v[124:127], v[204:207], v[152:155], v[124:127]
	v_mfma_f32_16x16x32_bf16 v[128:131], v[196:199], v[160:163], v[128:131]
	v_mfma_f32_16x16x32_bf16 v[132:135], v[204:207], v[160:163], v[132:135]
	v_mfma_f32_16x16x32_bf16 v[136:139], v[196:199], v[168:171], v[136:139]
	v_mfma_f32_16x16x32_bf16 v[140:143], v[204:207], v[168:171], v[140:143]
	v_mfma_f32_16x16x32_bf16 v[144:147], v[196:199], v[176:179], v[144:147]
	v_mfma_f32_16x16x32_bf16 v[148:151], v[204:207], v[176:179], v[148:151]
	v_mfma_f32_16x16x32_bf16 v[120:123], v[200:203], v[156:159], v[120:123]
	v_mfma_f32_16x16x32_bf16 v[124:127], v[208:211], v[156:159], v[124:127]
	v_mfma_f32_16x16x32_bf16 v[128:131], v[200:203], v[164:167], v[128:131]
	v_mfma_f32_16x16x32_bf16 v[132:135], v[208:211], v[164:167], v[132:135]
	v_mfma_f32_16x16x32_bf16 v[136:139], v[200:203], v[172:175], v[136:139]
	v_mfma_f32_16x16x32_bf16 v[140:143], v[208:211], v[172:175], v[140:143]
	v_mfma_f32_16x16x32_bf16 v[144:147], v[200:203], v[180:183], v[144:147]
	v_mfma_f32_16x16x32_bf16 v[148:151], v[208:211], v[180:183], v[148:151]
	s_setprio 0
	s_barrier
	s_sub_u32 s0, s0, 1
	s_cmp_lg_u32 s0, 0
	s_cbranch_scc1 .Lgyd_kloop
; #define LAS __attribute__((address_space(3)))
; #define BAR() { __builtin_amdgcn_sched_barrier(0); __builtin_amdgcn_s_barrier(); asm volatile("" ::: "memory"); __builtin_amdgcn_sched_barrier(0); }
; DI void gemm_stream2(const bf16_t* __restrict__ A, int lda, const bf16_t* __restrict__ Bt, int ldb, int K, int m0, int n0, ...
;     ...
;     for (int kt = 0; kt < nk; ++kt) {
;         const bool pf = (kt + 2 < nk) || has_next, more = (kt + 1 < nk) || has_next;
;         const bf16_t* pa = (kt + 2 < nk) ? ga + (kt + 2) * 64 : gan + (kt + 2 - nk) * 64;
;         const bf16_t* pb = (kt + 2 < nk) ? gb + (kt + 2) * 64 : gbn + (kt + 2 - nk) * 64;
;         const int plda = (kt + 2 < nk) ? lda : ldan, pldb = (kt + 2 < nk) ? ldb : ldbn;
;         const int s2 = st >= 1 ? st - 1 : 2;
;         const LAS char* base = lds + st * 49152;
; #pragma unroll
;         for (int ks = 0; ks < 2; ++ks) {
;             const unsigned fo = ks ? fo1 : fo0;
;             bf16x8 af[4], bfr[4];
; #pragma unroll
;             for (int i = 0; i < 4; ++i) { af[i] = *(const LAS bf16x8*)(base + aoff + i * 2048 + fo); bfr[i] = *(const LAS bf16x8*)(base + boff + i * 2048 + fo); }
;             if (ks == 1 && more) { if (pf) asm volatile("s_waitcnt vmcnt(3)" ::: "memory"); else asm volatile("s_waitcnt vmcnt(0)" ::: "memory"); }
;             if (pf) { PIECE(s2, ks * 3 + 0); PIECE(s2, ks * 3 + 1); PIECE(s2, ks * 3 + 2); }
;             asm volatile("s_waitcnt lgkmcnt(0)" ::: "memory");
;             BAR();
;             __builtin_amdgcn_s_setprio(1);
; #pragma unroll
;             for (int mi = 0; mi < 4; ++mi)
; #pragma unroll
;                 for (int ni = 0; ni < 4; ++ni) acc[mi][ni] = __builtin_amdgcn_mfma_f32_16x16x32_bf16(bfr[ni], af[mi], acc[mi][ni], 0, 0, 0);
;             __builtin_amdgcn_s_setprio(0);
;             BAR();
;         }
;         st = st == 2 ? 0 : st + 1;
;     }
;     if (grp == 0) BAR();
.Lgyd_kdone:
	s_cmp_lg_u32 s54, 0
	s_cbranch_scc1 .Lgyd_epi
	ds_read_b128 v[0:3], v188 offset:16
	ds_read_b128 v[4:7], v189 offset:16
	ds_read_b128 v[8:11], v188 offset:2064
	ds_read_b128 v[12:15], v189 offset:2064
	ds_read_b128 v[196:199], v188 offset:16400
	ds_read_b128 v[200:203], v189 offset:16400
	ds_read_b128 v[204:207], v188 offset:18448
	ds_read_b128 v[208:211], v189 offset:18448
	ds_read_b128 v[152:155], v186 offset:16
	ds_read_b128 v[156:159], v187 offset:16
	ds_read_b128 v[160:163], v186 offset:2064
	ds_read_b128 v[164:167], v187 offset:2064
	ds_read_b128 v[168:171], v186 offset:4112
	ds_read_b128 v[172:175], v187 offset:4112
	ds_read_b128 v[176:179], v186 offset:6160
	ds_read_b128 v[180:183], v187 offset:6160
	s_add_i32 m0, s39, 0x1c000
	s_nop 0
	global_load_lds_dwordx4 v184, s[72:73]
	s_add_i32 m0, s39, 0x1c400
	s_nop 0
	global_load_lds_dwordx4 v185, s[72:73]
	s_add_u32 s72, s72, 0x80
	s_addc_u32 s73, s73, 0
	s_add_i32 m0, s39, 0xc000
	s_nop 0
	global_load_lds_dwordx4 v184, s[68:69]
	s_add_i32 m0, s39, 0xc400
	s_nop 0
	global_load_lds_dwordx4 v185, s[68:69]
	s_add_u32 s68, s68, 0x80
	s_addc_u32 s69, s69, 0
	s_waitcnt lgkmcnt(0)
	s_waitcnt vmcnt(8)
	s_barrier
	s_setprio 1
	v_mfma_f32_16x16x32_bf16 v[24:27], v[0:3], v[152:155], v[24:27]
	v_mfma_f32_16x16x32_bf16 v[28:31], v[8:11], v[152:155], v[28:31]
	v_mfma_f32_16x16x32_bf16 v[32:35], v[0:3], v[160:163], v[32:35]
	v_mfma_f32_16x16x32_bf16 v[36:39], v[8:11], v[160:163], v[36:39]
	v_mfma_f32_16x16x32_bf16 v[40:43], v[0:3], v[168:171], v[40:43]
	v_mfma_f32_16x16x32_bf16 v[44:47], v[8:11], v[168:171], v[44:47]
	v_mfma_f32_16x16x32_bf16 v[48:51], v[0:3], v[176:179], v[48:51]
	v_mfma_f32_16x16x32_bf16 v[52:55], v[8:11], v[176:179], v[52:55]
	v_mfma_f32_16x16x32_bf16 v[24:27], v[4:7], v[156:159], v[24:27]
	v_mfma_f32_16x16x32_bf16 v[28:31], v[12:15], v[156:159], v[28:31]
	v_mfma_f32_16x16x32_bf16 v[32:35], v[4:7], v[164:167], v[32:35]
	v_mfma_f32_16x16x32_bf16 v[36:39], v[12:15], v[164:167], v[36:39]
	v_mfma_f32_16x16x32_bf16 v[40:43], v[4:7], v[172:175], v[40:43]
	v_mfma_f32_16x16x32_bf16 v[44:47], v[12:15], v[172:175], v[44:47]
	v_mfma_f32_16x16x32_bf16 v[48:51], v[4:7], v[180:183], v[48:51]
	v_mfma_f32_16x16x32_bf16 v[52:55], v[12:15], v[180:183], v[52:55]
	v_mfma_f32_16x16x32_bf16 v[56:59], v[196:199], v[152:155], v[56:59]
	v_mfma_f32_16x16x32_bf16 v[60:63], v[204:207], v[152:155], v[60:63]
	v_mfma_f32_16x16x32_bf16 v[64:67], v[196:199], v[160:163], v[64:67]
	v_mfma_f32_16x16x32_bf16 v[68:71], v[204:207], v[160:163], v[68:71]
	v_mfma_f32_16x16x32_bf16 v[72:75], v[196:199], v[168:171], v[72:75]
	v_mfma_f32_16x16x32_bf16 v[76:79], v[204:207], v[168:171], v[76:79]
	v_mfma_f32_16x16x32_bf16 v[80:83], v[196:199], v[176:179], v[80:83]
	v_mfma_f32_16x16x32_bf16 v[84:87], v[204:207], v[176:179], v[84:87]
	v_mfma_f32_16x16x32_bf16 v[56:59], v[200:203], v[156:159], v[56:59]
	v_mfma_f32_16x16x32_bf16 v[60:63], v[208:211], v[156:159], v[60:63]
	v_mfma_f32_16x16x32_bf16 v[64:67], v[200:203], v[164:167], v[64:67]
	v_mfma_f32_16x16x32_bf16 v[68:71], v[208:211], v[164:167], v[68:71]
	v_mfma_f32_16x16x32_bf16 v[72:75], v[200:203], v[172:175], v[72:75]
	v_mfma_f32_16x16x32_bf16 v[76:79], v[208:211], v[172:175], v[76:79]
	v_mfma_f32_16x16x32_bf16 v[80:83], v[200:203], v[180:183], v[80:83]
	v_mfma_f32_16x16x32_bf16 v[84:87], v[208:211], v[180:183], v[84:87]
	s_setprio 0
	s_barrier
	ds_read_b128 v[152:155], v186 offset:16400
	ds_read_b128 v[156:159], v187 offset:16400
	ds_read_b128 v[160:163], v186 offset:18448
	ds_read_b128 v[164:167], v187 offset:18448
	ds_read_b128 v[168:171], v186 offset:20496
	ds_read_b128 v[172:175], v187 offset:20496
	ds_read_b128 v[176:179], v186 offset:22544
	ds_read_b128 v[180:183], v187 offset:22544
	s_waitcnt lgkmcnt(0)
	s_waitcnt vmcnt(2)
	s_barrier
	s_setprio 1
	v_mfma_f32_16x16x32_bf16 v[88:91], v[0:3], v[152:155], v[88:91]
	v_mfma_f32_16x16x32_bf16 v[92:95], v[8:11], v[152:155], v[92:95]
	v_mfma_f32_16x16x32_bf16 v[96:99], v[0:3], v[160:163], v[96:99]
	v_mfma_f32_16x16x32_bf16 v[100:103], v[8:11], v[160:163], v[100:103]
	v_mfma_f32_16x16x32_bf16 v[104:107], v[0:3], v[168:171], v[104:107]
	v_mfma_f32_16x16x32_bf16 v[108:111], v[8:11], v[168:171], v[108:111]
	v_mfma_f32_16x16x32_bf16 v[112:115], v[0:3], v[176:179], v[112:115]
	v_mfma_f32_16x16x32_bf16 v[116:119], v[8:11], v[176:179], v[116:119]
	v_mfma_f32_16x16x32_bf16 v[88:91], v[4:7], v[156:159], v[88:91]
	v_mfma_f32_16x16x32_bf16 v[92:95], v[12:15], v[156:159], v[92:95]
	v_mfma_f32_16x16x32_bf16 v[96:99], v[4:7], v[164:167], v[96:99]
	v_mfma_f32_16x16x32_bf16 v[100:103], v[12:15], v[164:167], v[100:103]
	v_mfma_f32_16x16x32_bf16 v[104:107], v[4:7], v[172:175], v[104:107]
	v_mfma_f32_16x16x32_bf16 v[108:111], v[12:15], v[172:175], v[108:111]
	v_mfma_f32_16x16x32_bf16 v[112:115], v[4:7], v[180:183], v[112:115]
	v_mfma_f32_16x16x32_bf16 v[116:119], v[12:15], v[180:183], v[116:119]
	v_mfma_f32_16x16x32_bf16 v[120:123], v[196:199], v[152:155], v[120:123]
	v_mfma_f32_16x16x32_bf16 v[124:127], v[204:207], v[152:155], v[124:127]
	v_mfma_f32_16x16x32_bf16 v[128:131], v[196:199], v[160:163], v[128:131]
	v_mfma_f32_16x16x32_bf16 v[132:135], v[204:207], v[160:163], v[132:135]
	v_mfma_f32_16x16x32_bf16 v[136:139], v[196:199], v[168:171], v[136:139]
	v_mfma_f32_16x16x32_bf16 v[140:143], v[204:207], v[168:171], v[140:143]
	v_mfma_f32_16x16x32_bf16 v[144:147], v[196:199], v[176:179], v[144:147]
	v_mfma_f32_16x16x32_bf16 v[148:151], v[204:207], v[176:179], v[148:151]
	v_mfma_f32_16x16x32_bf16 v[120:123], v[200:203], v[156:159], v[120:123]
	v_mfma_f32_16x16x32_bf16 v[124:127], v[208:211], v[156:159], v[124:127]
	v_mfma_f32_16x16x32_bf16 v[128:131], v[200:203], v[164:167], v[128:131]
	v_mfma_f32_16x16x32_bf16 v[132:135], v[208:211], v[164:167], v[132:135]
	v_mfma_f32_16x16x32_bf16 v[136:139], v[200:203], v[172:175], v[136:139]
	v_mfma_f32_16x16x32_bf16 v[140:143], v[208:211], v[172:175], v[140:143]
	v_mfma_f32_16x16x32_bf16 v[144:147], v[200:203], v[180:183], v[144:147]
	v_mfma_f32_16x16x32_bf16 v[148:151], v[208:211], v[180:183], v[148:151]
	s_setprio 0
	s_barrier
; #define LAS __attribute__((address_space(3)))
; #define BAR() { __builtin_amdgcn_sched_barrier(0); __builtin_amdgcn_s_barrier(); asm volatile("" ::: "memory"); __builtin_amdgcn_sched_barrier(0); }
; DI void gemm_stream2(const bf16_t* __restrict__ A, int lda, const bf16_t* __restrict__ Bt, int ldb, int K, int m0, int n0, ...
;     ...
;         const int s2 = st >= 1 ? st - 1 : 2;
;         const LAS char* base = lds + st * 49152;
; #pragma unroll
;         for (int ks = 0; ks < 2; ++ks) {
;             const unsigned fo = ks ? fo1 : fo0;
;             bf16x8 af[4], bfr[4];
; #pragma unroll
;             for (int i = 0; i < 4; ++i) { af[i] = *(const LAS bf16x8*)(base + aoff + i * 2048 + fo); bfr[i] = *(const LAS bf16x8*)(base + boff + i * 2048 + fo); }
;             if (ks == 1 && more) { if (pf) asm volatile("s_waitcnt vmcnt(3)" ::: "memory"); else asm volatile("s_waitcnt vmcnt(0)" ::: "memory"); }
;             if (pf) { PIECE(s2, ks * 3 + 0); PIECE(s2, ks * 3 + 1); PIECE(s2, ks * 3 + 2); }
;             asm volatile("s_waitcnt lgkmcnt(0)" ::: "memory");
;             BAR();
;             __builtin_amdgcn_s_setprio(1);
; #pragma unroll
;             for (int mi = 0; mi < 4; ++mi)
; #pragma unroll
;                 for (int ni = 0; ni < 4; ++ni) acc[mi][ni] = __builtin_amdgcn_mfma_f32_16x16x32_bf16(bfr[ni], af[mi], acc[mi][ni], 0, 0, 0);
;             __builtin_amdgcn_s_setprio(0);
;             BAR();
;         }
;         st = st == 2 ? 0 : st + 1;
;     }
;     if (grp == 0) BAR();
	ds_read_b128 v[0:3], v188 offset:32784
	ds_read_b128 v[4:7], v189 offset:32784
	ds_read_b128 v[8:11], v188 offset:34832
	ds_read_b128 v[12:15], v189 offset:34832
	ds_read_b128 v[196:199], v188 offset:49168
	ds_read_b128 v[200:203], v189 offset:49168
	ds_read_b128 v[204:207], v188 offset:51216
	ds_read_b128 v[208:211], v189 offset:51216
	ds_read_b128 v[152:155], v186 offset:32784
	ds_read_b128 v[156:159], v187 offset:32784
	ds_read_b128 v[160:163], v186 offset:34832
	ds_read_b128 v[164:167], v187 offset:34832
	ds_read_b128 v[168:171], v186 offset:36880
	ds_read_b128 v[172:175], v187 offset:36880
	ds_read_b128 v[176:179], v186 offset:38928
	ds_read_b128 v[180:183], v187 offset:38928
	s_waitcnt lgkmcnt(0)
	s_waitcnt vmcnt(0)
	s_barrier
	s_setprio 1
	v_mfma_f32_16x16x32_bf16 v[24:27], v[0:3], v[152:155], v[24:27]
	v_mfma_f32_16x16x32_bf16 v[28:31], v[8:11], v[152:155], v[28:31]
	v_mfma_f32_16x16x32_bf16 v[32:35], v[0:3], v[160:163], v[32:35]
	v_mfma_f32_16x16x32_bf16 v[36:39], v[8:11], v[160:163], v[36:39]
	v_mfma_f32_16x16x32_bf16 v[40:43], v[0:3], v[168:171], v[40:43]
	v_mfma_f32_16x16x32_bf16 v[44:47], v[8:11], v[168:171], v[44:47]
	v_mfma_f32_16x16x32_bf16 v[48:51], v[0:3], v[176:179], v[48:51]
	v_mfma_f32_16x16x32_bf16 v[52:55], v[8:11], v[176:179], v[52:55]
	v_mfma_f32_16x16x32_bf16 v[24:27], v[4:7], v[156:159], v[24:27]
	v_mfma_f32_16x16x32_bf16 v[28:31], v[12:15], v[156:159], v[28:31]
	v_mfma_f32_16x16x32_bf16 v[32:35], v[4:7], v[164:167], v[32:35]
	v_mfma_f32_16x16x32_bf16 v[36:39], v[12:15], v[164:167], v[36:39]
	v_mfma_f32_16x16x32_bf16 v[40:43], v[4:7], v[172:175], v[40:43]
	v_mfma_f32_16x16x32_bf16 v[44:47], v[12:15], v[172:175], v[44:47]
	v_mfma_f32_16x16x32_bf16 v[48:51], v[4:7], v[180:183], v[48:51]
	v_mfma_f32_16x16x32_bf16 v[52:55], v[12:15], v[180:183], v[52:55]
	v_mfma_f32_16x16x32_bf16 v[56:59], v[196:199], v[152:155], v[56:59]
	v_mfma_f32_16x16x32_bf16 v[60:63], v[204:207], v[152:155], v[60:63]
	v_mfma_f32_16x16x32_bf16 v[64:67], v[196:199], v[160:163], v[64:67]
	v_mfma_f32_16x16x32_bf16 v[68:71], v[204:207], v[160:163], v[68:71]
	v_mfma_f32_16x16x32_bf16 v[72:75], v[196:199], v[168:171], v[72:75]
	v_mfma_f32_16x16x32_bf16 v[76:79], v[204:207], v[168:171], v[76:79]
	v_mfma_f32_16x16x32_bf16 v[80:83], v[196:199], v[176:179], v[80:83]
	v_mfma_f32_16x16x32_bf16 v[84:87], v[204:207], v[176:179], v[84:87]
	v_mfma_f32_16x16x32_bf16 v[56:59], v[200:203], v[156:159], v[56:59]
	v_mfma_f32_16x16x32_bf16 v[60:63], v[208:211], v[156:159], v[60:63]
	v_mfma_f32_16x16x32_bf16 v[64:67], v[200:203], v[164:167], v[64:67]
	v_mfma_f32_16x16x32_bf16 v[68:71], v[208:211], v[164:167], v[68:71]
	v_mfma_f32_16x16x32_bf16 v[72:75], v[200:203], v[172:175], v[72:75]
	v_mfma_f32_16x16x32_bf16 v[76:79], v[208:211], v[172:175], v[76:79]
	v_mfma_f32_16x16x32_bf16 v[80:83], v[200:203], v[180:183], v[80:83]
	v_mfma_f32_16x16x32_bf16 v[84:87], v[208:211], v[180:183], v[84:87]
	s_setprio 0
	s_barrier
	ds_read_b128 v[152:155], v186 offset:49168
	ds_read_b128 v[156:159], v187 offset:49168
	ds_read_b128 v[160:163], v186 offset:51216
	ds_read_b128 v[164:167], v187 offset:51216
	ds_read_b128 v[168:171], v186 offset:53264
	ds_read_b128 v[172:175], v187 offset:53264
	ds_read_b128 v[176:179], v186 offset:55312
	ds_read_b128 v[180:183], v187 offset:55312
	s_waitcnt lgkmcnt(0)
	s_barrier
	s_setprio 1
	v_mfma_f32_16x16x32_bf16 v[88:91], v[0:3], v[152:155], v[88:91]
	v_mfma_f32_16x16x32_bf16 v[92:95], v[8:11], v[152:155], v[92:95]
	v_mfma_f32_16x16x32_bf16 v[96:99], v[0:3], v[160:163], v[96:99]
	v_mfma_f32_16x16x32_bf16 v[100:103], v[8:11], v[160:163], v[100:103]
	v_mfma_f32_16x16x32_bf16 v[104:107], v[0:3], v[168:171], v[104:107]
	v_mfma_f32_16x16x32_bf16 v[108:111], v[8:11], v[168:171], v[108:111]
	v_mfma_f32_16x16x32_bf16 v[112:115], v[0:3], v[176:179], v[112:115]
	v_mfma_f32_16x16x32_bf16 v[116:119], v[8:11], v[176:179], v[116:119]
	v_mfma_f32_16x16x32_bf16 v[88:91], v[4:7], v[156:159], v[88:91]
	v_mfma_f32_16x16x32_bf16 v[92:95], v[12:15], v[156:159], v[92:95]
	v_mfma_f32_16x16x32_bf16 v[96:99], v[4:7], v[164:167], v[96:99]
	v_mfma_f32_16x16x32_bf16 v[100:103], v[12:15], v[164:167], v[100:103]
	v_mfma_f32_16x16x32_bf16 v[104:107], v[4:7], v[172:175], v[104:107]
	v_mfma_f32_16x16x32_bf16 v[108:111], v[12:15], v[172:175], v[108:111]
	v_mfma_f32_16x16x32_bf16 v[112:115], v[4:7], v[180:183], v[112:115]
	v_mfma_f32_16x16x32_bf16 v[116:119], v[12:15], v[180:183], v[116:119]
	v_mfma_f32_16x16x32_bf16 v[120:123], v[196:199], v[152:155], v[120:123]
	v_mfma_f32_16x16x32_bf16 v[124:127], v[204:207], v[152:155], v[124:127]
	v_mfma_f32_16x16x32_bf16 v[128:131], v[196:199], v[160:163], v[128:131]
	v_mfma_f32_16x16x32_bf16 v[132:135], v[204:207], v[160:163], v[132:135]
	v_mfma_f32_16x16x32_bf16 v[136:139], v[196:199], v[168:171], v[136:139]
	v_mfma_f32_16x16x32_bf16 v[140:143], v[204:207], v[168:171], v[140:143]
	v_mfma_f32_16x16x32_bf16 v[144:147], v[196:199], v[176:179], v[144:147]
	v_mfma_f32_16x16x32_bf16 v[148:151], v[204:207], v[176:179], v[148:151]
	v_mfma_f32_16x16x32_bf16 v[120:123], v[200:203], v[156:159], v[120:123]
	v_mfma_f32_16x16x32_bf16 v[124:127], v[208:211], v[156:159], v[124:127]
	v_mfma_f32_16x16x32_bf16 v[128:131], v[200:203], v[164:167], v[128:131]
	v_mfma_f32_16x16x32_bf16 v[132:135], v[208:211], v[164:167], v[132:135]
	v_mfma_f32_16x16x32_bf16 v[136:139], v[200:203], v[172:175], v[136:139]
	v_mfma_f32_16x16x32_bf16 v[140:143], v[208:211], v[172:175], v[140:143]
	v_mfma_f32_16x16x32_bf16 v[144:147], v[200:203], v[180:183], v[144:147]
	v_mfma_f32_16x16x32_bf16 v[148:151], v[208:211], v[180:183], v[148:151]
	s_setprio 0
	s_barrier
	s_cmp_lg_u32 s33, 0
	s_cbranch_scc1 .Lgyd_epi
	s_barrier

; #define BAR() { __builtin_amdgcn_sched_barrier(0); __builtin_amdgcn_s_barrier(); asm volatile("" ::: "memory"); __builtin_amdgcn_sched_barrier(0); }
; DI void gemm_stream2(const bf16_t* __restrict__ A, int lda, const bf16_t* __restrict__ Bt, int ldb, int K, int m0, int n0, ...
;     ...
;     const int wave = __builtin_amdgcn_readfirstlane(tid >> 6), lane = tid & 63, wm = wave >> 1, wn = wave & 1, r = lane & 15, q = lane >> 4;
;     const int sc0 = ((lane & 7) ^ (lane >> 4)) * 8, sc1 = ((lane & 7) ^ (4 | (lane >> 4))) * 8;
;     const bf16_t* ga = A + (size_t)(m0 + wave * 32 + (lane >> 3)) * lda;
;     const bf16_t* gb = Bt + (size_t)(n0 + wave * 16 + (lane >> 3)) * ldb;
;     const bf16_t* gan = An + (size_t)(m0n + wave * 32 + (lane >> 3)) * ldan;
;     const bf16_t* gbn = Btn + (size_t)(n0n + wave * 16 + (lane >> 3)) * ldbn;
;     const unsigned wa = (unsigned)wave * 4096u, wbb = 32768u + (unsigned)wave * 2048u;
;     ...
;     const int sw = r >> 1;
;     const unsigned fo0 = (unsigned)(r * 128 + ((q ^ sw) << 4)), fo1 = (unsigned)(r * 128 + (((q ^ sw) ^ 4) << 4));
;     const unsigned aoff = (unsigned)(wm * 64) * 128u, boff = 32768u + (unsigned)(wn * 64) * 128u;
;     const int nk = K / 64;
;     const int grp = wave >> 2;
;     ...
;     int st = rg.st;
;     if (!rg.primed) {
;         const int s1p = st == 2 ? 0 : st + 1;
;         BAR();
;         STAGE(st, 0);
;         STAGE(s1p, 1);
;         asm volatile("s_waitcnt vmcnt(6)" ::: "memory");
;         BAR();
;     }
;     if (grp == 1) BAR();
; DI void gemm_y(const Params& p, const bf16_t* A, int lda, size_t woff, int K, int kper, int bid, int nb, char* smem, const int tid) {
;     ...
;     for (; have; tm = tm2, tn = tn2) {
;         have = ti.next(tm2, tn2);
;         const int m0 = tm * 256, n0 = tn * 128;
;         f32x4 acc[4][4]; zero_acc(acc);
;         gemm_stream(A, lda, Bt, K, K, m0, n0, have, tm2 * 256, tn2 * 128, smem, acc, tid, rg);
.Lgyo_lanes:
	v_and_b32_e32 v190, 63, v193
	v_and_b32_e32 v191, 15, v190
	v_lshrrev_b32_e32 v17, 4, v190
	v_lshrrev_b32_e32 v18, 3, v190
	v_and_b32_e32 v19, 7, v190
	v_xor_b32_e32 v195, v19, v17
	v_lshlrev_b32_e32 v195, 4, v195
	s_mov_b32 s1, 0x800
	v_mad_u32_u24 v184, v18, s1, v195
	v_or_b32_e32 v195, 4, v17
	v_xor_b32_e32 v195, v19, v195
	v_lshlrev_b32_e32 v195, 4, v195
	v_add_u32_e32 v227, 8, v18
	v_mad_u32_u24 v185, v227, s1, v195
	v_lshrrev_b32_e32 v195, 1, v191
	v_xor_b32_e32 v195, v17, v195
	v_lshlrev_b32_e32 v195, 4, v195
	s_lshl_b32 s1, s33, 6
	v_add_u32_e32 v227, s1, v191
	v_lshl_add_u32 v186, v227, 7, v195
	v_xor_b32_e32 v187, 64, v186
	v_lshlrev_b32_e32 v228, 11, v227
	s_lshl_b32 s1, s36, 5
	v_add_u32_e32 v227, s1, v191
	v_lshl_add_u32 v188, v227, 7, v195
	v_add_u32_e32 v188, 0x10000, v188
	v_xor_b32_e32 v189, 64, v188
	s_lshl_b32 s1, s36, 6
	v_lshl_add_u32 v229, v17, 3, s1
	v_add_u32_e32 v237, v228, v229
	v_and_b32_e32 v227, 1, v17
	v_mul_u32_u24_e32 v227, 0x7ff8, v227
	v_add_u32_e32 v236, v237, v227
	s_add_i32 m0, s39, 0x10000
	s_nop 0
	global_load_lds_dwordx4 v184, s[70:71]
	s_add_i32 m0, s39, 0x10400
	s_nop 0
	global_load_lds_dwordx4 v185, s[70:71]
	s_add_u32 s70, s70, 0x80
	s_addc_u32 s71, s71, 0
	s_add_i32 m0, s39, 0x0
	s_nop 0
	global_load_lds_dwordx4 v184, s[66:67]
	s_add_i32 m0, s39, 0x400
	s_nop 0
	global_load_lds_dwordx4 v185, s[66:67]
	s_add_u32 s66, s66, 0x80
	s_addc_u32 s67, s67, 0
	s_add_i32 m0, s39, 0x14000
	s_nop 0
	global_load_lds_dwordx4 v184, s[72:73]
	s_add_i32 m0, s39, 0x14400
	s_nop 0
	global_load_lds_dwordx4 v185, s[72:73]
	s_add_u32 s72, s72, 0x80
	s_addc_u32 s73, s73, 0
	s_add_i32 m0, s39, 0x4000
	s_nop 0
	global_load_lds_dwordx4 v184, s[68:69]
	s_add_i32 m0, s39, 0x4400
	s_nop 0
	global_load_lds_dwordx4 v185, s[68:69]
	s_add_u32 s68, s68, 0x80
	s_addc_u32 s69, s69, 0
	s_add_i32 m0, s39, 0x18000
	s_nop 0
	global_load_lds_dwordx4 v184, s[70:71]
	s_add_i32 m0, s39, 0x18400
	s_nop 0
	global_load_lds_dwordx4 v185, s[70:71]
	s_add_u32 s70, s70, 0x80
	s_addc_u32 s71, s71, 0
	s_add_i32 m0, s39, 0x8000
	s_nop 0
	global_load_lds_dwordx4 v184, s[66:67]
	s_add_i32 m0, s39, 0x8400
	s_nop 0
	global_load_lds_dwordx4 v185, s[66:67]
	s_add_u32 s66, s66, 0x80
	s_addc_u32 s67, s67, 0
	s_waitcnt vmcnt(6)
	s_barrier
	s_cmp_eq_u32 s33, 0
	s_cbranch_scc1 .Lgyo_lead
	s_barrier

; #define BAR() { __builtin_amdgcn_sched_barrier(0); __builtin_amdgcn_s_barrier(); asm volatile("" ::: "memory"); __builtin_amdgcn_sched_barrier(0); }
; DI void gemm_stream2(const bf16_t* __restrict__ A, int lda, const bf16_t* __restrict__ Bt, int ldb, int K, int m0, int n0, ...
;     ...
;     const int wave = __builtin_amdgcn_readfirstlane(tid >> 6), lane = tid & 63, wm = wave >> 1, wn = wave & 1, r = lane & 15, q = lane >> 4;
;     const int sc0 = ((lane & 7) ^ (lane >> 4)) * 8, sc1 = ((lane & 7) ^ (4 | (lane >> 4))) * 8;
;     const bf16_t* ga = A + (size_t)(m0 + wave * 32 + (lane >> 3)) * lda;
;     const bf16_t* gb = Bt + (size_t)(n0 + wave * 16 + (lane >> 3)) * ldb;
;     const bf16_t* gan = An + (size_t)(m0n + wave * 32 + (lane >> 3)) * ldan;
;     const bf16_t* gbn = Btn + (size_t)(n0n + wave * 16 + (lane >> 3)) * ldbn;
;     const unsigned wa = (unsigned)wave * 4096u, wbb = 32768u + (unsigned)wave * 2048u;
;     ...
;     const int sw = r >> 1;
;     const unsigned fo0 = (unsigned)(r * 128 + ((q ^ sw) << 4)), fo1 = (unsigned)(r * 128 + (((q ^ sw) ^ 4) << 4));
;     const unsigned aoff = (unsigned)(wm * 64) * 128u, boff = 32768u + (unsigned)(wn * 64) * 128u;
;     const int nk = K / 64;
;     const int grp = wave >> 2;
;     ...
;     int st = rg.st;
;     if (!rg.primed) {
;         const int s1p = st == 2 ? 0 : st + 1;
;         BAR();
;         STAGE(st, 0);
;         STAGE(s1p, 1);
;         asm volatile("s_waitcnt vmcnt(6)" ::: "memory");
;         BAR();
;     }
;     if (grp == 1) BAR();
; DI void gemm_in(const Params& p, int l, int bid, int nb, char* smem, const int tid) {
;     ...
;     for (; have; tm = tm2, tn = tn2) {
;         have = ti.next(tm2, tn2);
;         const int m0 = tm * 256, n0 = tn * 128;
;         f32x4 acc[4][4]; zero_acc(acc);
;         gemm_stream(A, 1024, Bt, 1024, 1024, m0, n0, have, tm2 * 256, tn2 * 128, smem, acc, tid, rg);
.Lin_ranged:
	s_cmp_ge_u32 s51, s52
	s_cbranch_scc1 .Lin_stub
	v_and_b32_e32 v190, 63, v193
	v_and_b32_e32 v191, 15, v190
	v_lshrrev_b32_e32 v17, 4, v190
	v_lshrrev_b32_e32 v18, 3, v190
	v_and_b32_e32 v19, 7, v190
	v_xor_b32_e32 v195, v19, v17
	v_lshlrev_b32_e32 v195, 4, v195
	v_lshl_add_u32 v184, v18, 11, v195
	v_or_b32_e32 v195, 4, v17
	v_xor_b32_e32 v195, v19, v195
	v_lshlrev_b32_e32 v195, 4, v195
	v_add_u32_e32 v227, 8, v18
	v_lshl_add_u32 v185, v227, 11, v195
	v_lshrrev_b32_e32 v195, 1, v191
	v_xor_b32_e32 v195, v17, v195
	v_lshlrev_b32_e32 v195, 4, v195
	s_lshl_b32 s1, s33, 6
	v_add_u32_e32 v230, s1, v191
	v_lshl_add_u32 v186, v230, 7, v195
	v_xor_b32_e32 v187, 64, v186
	s_lshl_b32 s1, s36, 5
	v_add_u32_e32 v227, s1, v191
	v_lshl_add_u32 v188, v227, 7, v195
	v_add_u32_e32 v188, 0x10000, v188
	v_xor_b32_e32 v189, 64, v188
	s_lshl_b32 s1, s36, 7
	v_lshl_add_u32 v236, v17, 4, s1
	v_lshrrev_b32_e32 v228, 1, v236
	v_lshl_add_u32 v237, v230, 9, v228
	v_and_b32_e32 v227, 1, v17
	v_mul_u32_u24_e32 v227, 0x1ff8, v227
	v_add_u32_e32 v229, v237, v227
	s_lshr_b32 s1, s51, 6
	s_and_b32 s2, s51, 63
	s_lshr_b32 s58, s2, 3
	s_and_b32 s2, s2, 7
	s_lshl_b32 s1, s1, 3
	s_add_i32 s57, s1, s2
	s_lshl_b32 s1, s57, 19
	s_lshl_b32 s2, s10, 15
	s_add_u32 s1, s1, s2
	s_add_u32 s1, s1, 0x3240000
	s_add_u32 s66, s88, s1
	s_addc_u32 s67, s89, 0
	s_add_u32 s68, s66, 0x40000
	s_addc_u32 s69, s67, 0
	s_lshl_b32 s1, s58, 19
	s_add_u32 s1, s1, s2
	s_add_u32 s1, s1, s61
	s_add_u32 s70, s88, s1
	s_addc_u32 s71, s89, 0
	s_add_u32 s72, s70, 0x40000
	s_addc_u32 s73, s71, 0
	s_add_i32 m0, s39, 0x10000
	s_nop 0
	global_load_lds_dwordx4 v184, s[70:71]
	s_add_i32 m0, s39, 0x10400
	s_nop 0
	global_load_lds_dwordx4 v185, s[70:71]
	s_add_u32 s70, s70, 0x80
	s_addc_u32 s71, s71, 0
	s_add_i32 m0, s39, 0x0
	s_nop 0
	global_load_lds_dwordx4 v184, s[66:67]
	s_add_i32 m0, s39, 0x400
	s_nop 0
	global_load_lds_dwordx4 v185, s[66:67]
	s_add_u32 s66, s66, 0x80
	s_addc_u32 s67, s67, 0
	s_add_i32 m0, s39, 0x14000
	s_nop 0
	global_load_lds_dwordx4 v184, s[72:73]
	s_add_i32 m0, s39, 0x14400
	s_nop 0
	global_load_lds_dwordx4 v185, s[72:73]
	s_add_u32 s72, s72, 0x80
	s_addc_u32 s73, s73, 0
	s_add_i32 m0, s39, 0x4000
	s_nop 0
	global_load_lds_dwordx4 v184, s[68:69]
	s_add_i32 m0, s39, 0x4400
	s_nop 0
	global_load_lds_dwordx4 v185, s[68:69]
	s_add_u32 s68, s68, 0x80
	s_addc_u32 s69, s69, 0
	s_add_i32 m0, s39, 0x18000
	s_nop 0
	global_load_lds_dwordx4 v184, s[70:71]
	s_add_i32 m0, s39, 0x18400
	s_nop 0
	global_load_lds_dwordx4 v185, s[70:71]
	s_add_u32 s70, s70, 0x80
	s_addc_u32 s71, s71, 0
	s_add_i32 m0, s39, 0x8000
	s_nop 0
	global_load_lds_dwordx4 v184, s[66:67]
	s_add_i32 m0, s39, 0x8400
	s_nop 0
	global_load_lds_dwordx4 v185, s[66:67]
	s_add_u32 s66, s66, 0x80
	s_addc_u32 s67, s67, 0
	s_waitcnt vmcnt(6)
	s_barrier
	s_cmp_eq_u32 s33, 0
	s_cbranch_scc1 .Lin_lead
	s_barrier
